# bias hoist (P0,mlp1) + relaxed first-iteration vmcnt waits after epilogue stores (P0, mlp1, chain)
# baseline (speedup 1.0000x reference)
; #define GAS __attribute__((address_space(1)))
; #define PG8_WAIT_V(n) asm volatile("s_waitcnt vmcnt(" #n ")" ::: "memory")
; #define PG8_BAR __builtin_amdgcn_s_barrier()
; template <class Epi, class Sched, bool ALIGN_EPI, bool SP2>
; __device__ __forceinline__ void gemm_phase(LAS unsigned char* lds, const int tid, const Gemm g, const Sched& S, const Epi& E) {
;     ...
;     for (int i = 0; i < 2; ++i) { int R, C; stage_rc(tid * 16 + i * 8192, R, C); const int Rb = Epi::PERM ? ((R & ~31) + perm32(R & 31)) : R;
;         voffA[i] = (unsigned)(R * g.lda + C) * 2u; voffB[i] = (unsigned)(Rb * g.ldb + C) * 2u; }
;     const size_t kstep = (size_t)(BK * 2);
;     const size_t hstepA = (size_t)HALF * g.lda * 2, hstepB = (size_t)HALF * g.ldb * 2;
;     const unsigned ldsw = (unsigned)wid * 1024u;
;     const int aoff = lds_byte(wr * 64 + fr, fq * 8), boff = lds_byte(wc * 32 + fr, fq * 8);
;     ...
;     Unit cur, nxt; int ui = 0;
;     if (!S.next(0, cur)) return;
;     if (wr == 1) __builtin_amdgcn_s_setprio(1);
;     f32x4 acc[2][2][4][2];
; #pragma unroll
;     for (int a = 0; a < 2; ++a)
; #pragma unroll
;         for (int b = 0; b < 2; ++b)
; #pragma unroll
;             for (int m = 0; m < 4; ++m)
; #pragma unroll
;                 for (int n = 0; n < 2; ++n) acc[a][b][m][n] = (f32x4){0.f, 0.f, 0.f, 0.f};
;     bf16x8 At[4][2], B0[2][2], B1[2][2];
;     const GAS char* cA = S.aptr(cur); const GAS char* cB = S.bptr(cur);
;     if constexpr (SP2) {
;         PG8_STAGE(PG8_SB(0, 0), cB, voffB); PG8_STAGE(PG8_SB(0, 1), cB + hstepB, voffB); PG8_STAGE(PG8_SA(0, 0), cA, voffA); PG8_STAGE(PG8_SA(0, 1), cA + hstepA, voffA);
;         if (wr == 1) PG8_BAR;
;         PG8_WAIT_V(2); PG8_BAR;
;         PG8_STAGE(PG8_SB(1, 0), cB + kstep, voffB); PG8_STAGE(PG8_SA(1, 0), cA + kstep, voffA); PG8_STAGE(PG8_SB(1, 1), cB + hstepB + kstep, voffB);
;         PG8_WAIT_V(6); PG8_BAR;
;     __device__ __forceinline__ void operator()(const f32x4 (&acc)[2][2][4][2], const Unit& u, int wr, int wc, int fr, int fq) const {
;     ...
;         for (int ai = 0; ai < 2; ++ai)
; #pragma unroll
;             for (int m = 0; m < 4; ++m) { GAS bf16_t* rowp = O + (size_t)(row0 + ai * HALF + m * 16) * ldc + col0;
; #pragma unroll
;                 for (int bj = 0; bj < 2; ++bj) { f32x4 v0 = acc[ai][bj][m][0] + bv[bj][0], v1 = acc[ai][bj][m][1] + bv[bj][1];
.LBB0_458:
	s_add_u32 s8, s8, 0x2a600000
	s_addc_u32 s9, s9, 0
	s_lshl_b64 s[12:13], s[56:57], 2
	s_waitcnt lgkmcnt(0)
	s_add_u32 s10, s10, s12
	s_addc_u32 s11, s11, s13
	s_lshl_b32 s12, s19, 5
	s_and_b32 s19, s12, 0x60
	s_add_i32 m0, s48, 0x18000
	v_lshl_add_u64 v[2:3], v[2:3], 0, s[14:15]
	s_lshl_b32 s22, s18, 13
	s_lshl_b32 s23, s19, 7
	s_waitcnt vmcnt(2)
	s_barrier
	global_load_lds_dwordx4 v[2:3], off
	v_lshl_add_u64 v[2:3], v[4:5], 0, s[14:15]
	s_add_i32 m0, s48, 0x1a000
	s_add_i32 s52, s48, 0x8000
	s_add_i32 s53, s48, 0xa000
	global_load_lds_dwordx4 v[2:3], off
	v_lshl_add_u64 v[2:3], v[6:7], 0, s[14:15]
	s_mov_b32 m0, s52
	s_add_u32 s12, s34, 0x80080
	global_load_lds_dwordx4 v[2:3], off
	v_lshl_add_u64 v[2:3], v[8:9], 0, s[14:15]
	s_mov_b32 m0, s53
	s_addc_u32 s13, s35, 0
	global_load_lds_dwordx4 v[2:3], off
	s_add_i32 m0, s48, 0x1c000
	v_lshl_add_u64 v[2:3], s[12:13], 0, v[202:203]
	global_load_lds_dwordx4 v[2:3], off
	v_lshl_add_u64 v[2:3], s[12:13], 0, v[150:151]
	s_add_i32 m0, s48, 0x1e000
	s_cmp_lg_u64 s[10:11], 0
	global_load_lds_dwordx4 v[2:3], off
	v_lshrrev_b32_e32 v3, 1, v0
	v_and_b32_e32 v3, 24, v3
	v_and_b32_e32 v2, 15, v0
	v_lshlrev_b32_e32 v4, 1, v3
	v_lshl_or_b32 v1, s18, 6, v2
	v_lshl_or_b32 v2, v2, 6, v4
	v_lshlrev_b32_e32 v4, 2, v0
	v_and_b32_e32 v4, 32, v4
	v_bitop3_b32 v5, v2, s22, v4 bitop3:0xde
	v_bitop3_b32 v160, s23, v2, v4 bitop3:0xf6
	v_lshlrev_b32_e32 v2, 15, v13
	v_and_b32_e32 v2, 0xffff0000, v2
	v_or_b32_e32 v161, s19, v3
	v_lshl_add_u32 v2, v14, 12, v2
	v_and_b32_e32 v3, 1, v13
	v_lshl_or_b32 v2, v3, 6, v2
	v_lshl_add_u32 v152, v15, 1, v2
	v_lshlrev_b32_e32 v2, 15, v10
	v_and_b32_e32 v2, 0xffff0000, v2
	s_waitcnt vmcnt(6)
	v_lshl_add_u32 v2, v11, 12, v2
	v_and_b32_e32 v3, 1, v10
	v_lshl_or_b32 v2, v3, 6, v2
	v_readlane_b32 s18, v254, 63
	s_cselect_b64 s[12:13], -1, 0
	v_mov_b32_e32 v153, v203
	v_lshl_add_u32 v154, v12, 1, v2
	v_mov_b32_e32 v155, v203
	s_mov_b32 s54, 0
	v_add_u32_e32 v162, 0, v5
	v_readlane_b32 s56, v255, 15
	s_mov_b32 s55, s18
	s_barrier
	v_readlane_b32 s19, v255, 0
	s_mov_b32 s100, 0
	s_branch .LBB0_460
.LBB0_459:
	v_lshl_add_u32 v163, s55, 8, v1
	v_mov_b64_e32 v[156:157], s[8:9]
	v_mad_i64_i32 v[164:165], s[34:35], v163, s74, v[156:157]
	v_lshlrev_b64 v[158:159], 1, v[158:159]
	v_lshl_add_u64 v[164:165], v[164:165], 0, v[158:159]
	v_pk_add_f32 v[128:129], v[128:129], v[230:231]
	v_pk_add_f32 v[126:127], v[126:127], v[228:229]
	v_pk_add_f32 v[166:167], v[124:125], v[234:235]
	v_pk_add_f32 v[124:125], v[122:123], v[232:233]
	v_cvt_pk_bf16_f32 v122, v126, v127
	v_cvt_pk_bf16_f32 v123, v128, v129
	v_pk_add_f32 v[118:119], v[118:119], v[236:237]
	v_cvt_pk_bf16_f32 v124, v124, v125
	v_cvt_pk_bf16_f32 v125, v166, v167
	global_store_dwordx4 v[164:165], v[122:125], off
	v_pk_add_f32 v[120:121], v[120:121], v[238:239]
	v_pk_add_f32 v[114:115], v[114:115], v[228:229]
	v_pk_add_f32 v[122:123], v[112:113], v[242:243]
	v_pk_add_f32 v[112:113], v[110:111], v[240:241]
	v_cvt_pk_bf16_f32 v110, v118, v119
	v_cvt_pk_bf16_f32 v111, v120, v121
	v_pk_add_f32 v[102:103], v[102:103], v[236:237]
	v_cvt_pk_bf16_f32 v112, v112, v113
	v_cvt_pk_bf16_f32 v113, v122, v123
	global_store_dwordx4 v[164:165], v[110:113], off offset:256
	v_pk_add_f32 v[104:105], v[104:105], v[238:239]
	v_pk_add_f32 v[98:99], v[98:99], v[228:229]
	v_or_b32_e32 v110, 16, v163
	v_mad_i64_i32 v[110:111], s[34:35], v110, s74, v[156:157]
	v_lshl_add_u64 v[110:111], v[110:111], 0, v[158:159]
	v_pk_add_f32 v[112:113], v[116:117], v[230:231]
	v_pk_add_f32 v[116:117], v[108:109], v[234:235]
	v_pk_add_f32 v[108:109], v[106:107], v[232:233]
	v_cvt_pk_bf16_f32 v106, v114, v115
	v_cvt_pk_bf16_f32 v107, v112, v113
	v_pk_add_f32 v[86:87], v[86:87], v[236:237]
	v_cvt_pk_bf16_f32 v108, v108, v109
	v_cvt_pk_bf16_f32 v109, v116, v117
	global_store_dwordx4 v[110:111], v[106:109], off
	v_pk_add_f32 v[88:89], v[88:89], v[238:239]
	v_pk_add_f32 v[82:83], v[82:83], v[228:229]
	v_pk_add_f32 v[106:107], v[96:97], v[242:243]
	v_pk_add_f32 v[96:97], v[94:95], v[240:241]
	v_cvt_pk_bf16_f32 v94, v102, v103
	v_cvt_pk_bf16_f32 v95, v104, v105
	v_pk_add_f32 v[70:71], v[70:71], v[236:237]
	v_cvt_pk_bf16_f32 v96, v96, v97
	v_cvt_pk_bf16_f32 v97, v106, v107
	global_store_dwordx4 v[110:111], v[94:97], off offset:256
	v_pk_add_f32 v[72:73], v[72:73], v[238:239]
	v_pk_add_f32 v[64:65], v[64:65], v[230:231]
	v_or_b32_e32 v94, 32, v163
	v_mad_i64_i32 v[94:95], s[34:35], v94, s74, v[156:157]
	v_lshl_add_u64 v[94:95], v[94:95], 0, v[158:159]
	v_pk_add_f32 v[96:97], v[100:101], v[230:231]
	v_pk_add_f32 v[100:101], v[92:93], v[234:235]
	v_pk_add_f32 v[92:93], v[90:91], v[232:233]
	v_cvt_pk_bf16_f32 v90, v98, v99
	v_cvt_pk_bf16_f32 v91, v96, v97
	v_pk_add_f32 v[62:63], v[62:63], v[228:229]
; #define GAS __attribute__((address_space(1)))
; __device__ __forceinline__ unsigned cvt_pk_bf16(float lo, float hi) { unsigned r; asm volatile("v_cvt_pk_bf16_f32 %0, %1, %2" : "=v"(r) : "v"(lo), "v"(hi)); return r; }
;     __device__ __forceinline__ void operator()(const f32x4 (&acc)[2][2][4][2], const Unit& u, int wr, int wc, int fr, int fq) const {
;     ...
;         for (int ai = 0; ai < 2; ++ai)
; #pragma unroll
;             for (int m = 0; m < 4; ++m) { GAS bf16_t* rowp = O + (size_t)(row0 + ai * HALF + m * 16) * ldc + col0;
; #pragma unroll
;                 for (int bj = 0; bj < 2; ++bj) { f32x4 v0 = acc[ai][bj][m][0] + bv[bj][0], v1 = acc[ai][bj][m][1] + bv[bj][1];
;                     if (ACT == 1) {
; #pragma unroll
;                         for (int j = 0; j < 4; ++j) { const float a = fmaxf(v0[j], 0.f), b = fmaxf(v1[j], 0.f); v0[j] = a * a; v1[j] = b * b; } }
;                     u32x4 w; w.x = cvt_pk_bf16(v0[0], v0[1]); w.y = cvt_pk_bf16(v0[2], v0[3]); w.z = cvt_pk_bf16(v1[0], v1[1]); w.w = cvt_pk_bf16(v1[2], v1[3]);
;                     *(GAS u32x4*)(rowp + bj * HALF) = w; } }
	v_cvt_pk_bf16_f32 v92, v92, v93
	v_cvt_pk_bf16_f32 v93, v100, v101
	global_store_dwordx4 v[94:95], v[90:93], off
	v_pk_add_f32 v[54:55], v[54:55], v[236:237]
	v_pk_add_f32 v[56:57], v[56:57], v[238:239]
	v_pk_add_f32 v[90:91], v[80:81], v[242:243]
	v_pk_add_f32 v[80:81], v[78:79], v[240:241]
	v_cvt_pk_bf16_f32 v78, v86, v87
	v_cvt_pk_bf16_f32 v79, v88, v89
	v_pk_add_f32 v[50:51], v[50:51], v[228:229]
	v_cvt_pk_bf16_f32 v80, v80, v81
	v_cvt_pk_bf16_f32 v81, v90, v91
	global_store_dwordx4 v[94:95], v[78:81], off offset:256
	v_pk_add_f32 v[38:39], v[38:39], v[236:237]
	v_pk_add_f32 v[40:41], v[40:41], v[238:239]
	v_or_b32_e32 v78, 48, v163
	v_mad_i64_i32 v[78:79], s[34:35], v78, s74, v[156:157]
	v_lshl_add_u64 v[78:79], v[78:79], 0, v[158:159]
	v_pk_add_f32 v[80:81], v[84:85], v[230:231]
	v_pk_add_f32 v[84:85], v[76:77], v[234:235]
	v_pk_add_f32 v[76:77], v[74:75], v[232:233]
	v_cvt_pk_bf16_f32 v74, v82, v83
	v_cvt_pk_bf16_f32 v75, v80, v81
	v_pk_add_f32 v[34:35], v[34:35], v[228:229]
	v_cvt_pk_bf16_f32 v76, v76, v77
	v_cvt_pk_bf16_f32 v77, v84, v85
	global_store_dwordx4 v[78:79], v[74:77], off
	v_pk_add_f32 v[22:23], v[22:23], v[236:237]
	v_pk_add_f32 v[24:25], v[24:25], v[238:239]
	v_pk_add_f32 v[74:75], v[68:69], v[242:243]
	v_pk_add_f32 v[68:69], v[66:67], v[240:241]
	v_cvt_pk_bf16_f32 v66, v70, v71
	v_cvt_pk_bf16_f32 v67, v72, v73
	v_pk_add_f32 v[18:19], v[18:19], v[228:229]
	v_cvt_pk_bf16_f32 v68, v68, v69
	v_cvt_pk_bf16_f32 v69, v74, v75
	global_store_dwordx4 v[78:79], v[66:69], off offset:256
	s_and_b64 vcc, exec, s[38:39]
	s_mov_b32 s56, s18
	v_add_u32_e32 v66, 0x80, v163
	v_mad_i64_i32 v[66:67], s[34:35], v66, s74, v[156:157]
	v_lshl_add_u64 v[66:67], v[66:67], 0, v[158:159]
	v_pk_add_f32 v[68:69], v[60:61], v[234:235]
	v_pk_add_f32 v[60:61], v[58:59], v[232:233]
	v_cvt_pk_bf16_f32 v58, v62, v63
	v_cvt_pk_bf16_f32 v59, v64, v65
	s_mov_b32 s55, s22
	v_cvt_pk_bf16_f32 v60, v60, v61
	v_cvt_pk_bf16_f32 v61, v68, v69
	global_store_dwordx4 v[66:67], v[58:61], off
	s_mov_b64 s[40:41], s[24:25]
	v_pk_add_f32 v[8:9], v[8:9], v[238:239]
	v_pk_add_f32 v[58:59], v[48:49], v[242:243]
	v_pk_add_f32 v[48:49], v[46:47], v[240:241]
	v_cvt_pk_bf16_f32 v46, v54, v55
	v_cvt_pk_bf16_f32 v47, v56, v57
	v_pk_add_f32 v[6:7], v[6:7], v[236:237]
	v_cvt_pk_bf16_f32 v48, v48, v49
	v_cvt_pk_bf16_f32 v49, v58, v59
	global_store_dwordx4 v[66:67], v[46:49], off offset:256
	s_nop 1
	v_add_u32_e32 v46, 0x90, v163
	v_mad_i64_i32 v[46:47], s[34:35], v46, s74, v[156:157]
	v_lshl_add_u64 v[46:47], v[46:47], 0, v[158:159]
	v_pk_add_f32 v[48:49], v[52:53], v[230:231]
	v_pk_add_f32 v[52:53], v[44:45], v[234:235]
	v_pk_add_f32 v[44:45], v[42:43], v[232:233]
	v_cvt_pk_bf16_f32 v42, v50, v51
	v_cvt_pk_bf16_f32 v43, v48, v49
	s_nop 0
	v_cvt_pk_bf16_f32 v44, v44, v45
	v_cvt_pk_bf16_f32 v45, v52, v53
	global_store_dwordx4 v[46:47], v[42:45], off
	s_nop 1
	v_pk_add_f32 v[42:43], v[32:33], v[242:243]
	v_pk_add_f32 v[32:33], v[30:31], v[240:241]
	v_cvt_pk_bf16_f32 v30, v38, v39
	v_cvt_pk_bf16_f32 v31, v40, v41
	s_nop 0
	v_cvt_pk_bf16_f32 v32, v32, v33
	v_cvt_pk_bf16_f32 v33, v42, v43
	global_store_dwordx4 v[46:47], v[30:33], off offset:256
	s_nop 1
	v_add_u32_e32 v30, 0xa0, v163
	v_mad_i64_i32 v[30:31], s[34:35], v30, s74, v[156:157]
	v_lshl_add_u64 v[30:31], v[30:31], 0, v[158:159]
	v_pk_add_f32 v[32:33], v[36:37], v[230:231]
	v_pk_add_f32 v[36:37], v[28:29], v[234:235]
	v_pk_add_f32 v[28:29], v[26:27], v[232:233]
	v_cvt_pk_bf16_f32 v26, v34, v35
	v_cvt_pk_bf16_f32 v27, v32, v33
	s_nop 0
	v_cvt_pk_bf16_f32 v28, v28, v29
	v_cvt_pk_bf16_f32 v29, v36, v37
	global_store_dwordx4 v[30:31], v[26:29], off
	s_nop 1
	v_pk_add_f32 v[26:27], v[16:17], v[242:243]
	v_pk_add_f32 v[16:17], v[14:15], v[240:241]
	v_cvt_pk_bf16_f32 v14, v22, v23
	v_cvt_pk_bf16_f32 v15, v24, v25
	s_nop 0
	v_cvt_pk_bf16_f32 v16, v16, v17
	v_cvt_pk_bf16_f32 v17, v26, v27
	global_store_dwordx4 v[30:31], v[14:17], off offset:256
	s_nop 1
	v_add_u32_e32 v14, 0xb0, v163
	v_mad_i64_i32 v[14:15], s[34:35], v14, s74, v[156:157]
	v_lshl_add_u64 v[14:15], v[14:15], 0, v[158:159]
	v_pk_add_f32 v[16:17], v[20:21], v[230:231]
	v_pk_add_f32 v[20:21], v[12:13], v[234:235]
	v_pk_add_f32 v[12:13], v[10:11], v[232:233]
	v_cvt_pk_bf16_f32 v10, v18, v19
	v_cvt_pk_bf16_f32 v11, v16, v17
	s_mov_b64 s[34:35], s[26:27]
	v_cvt_pk_bf16_f32 v12, v12, v13
	v_cvt_pk_bf16_f32 v13, v20, v21
	global_store_dwordx4 v[14:15], v[10:13], off
	s_nop 1
	v_pk_add_f32 v[10:11], v[4:5], v[242:243]
	v_pk_add_f32 v[4:5], v[2:3], v[240:241]
	v_cvt_pk_bf16_f32 v2, v6, v7
	v_cvt_pk_bf16_f32 v3, v8, v9
	s_nop 0
	v_cvt_pk_bf16_f32 v4, v4, v5
	v_cvt_pk_bf16_f32 v5, v10, v11
	global_store_dwordx4 v[14:15], v[2:5], off offset:256
	s_cbranch_vccnz .LBB0_472
	s_mov_b32 s100, 1

; #define PG8_STAGE(bufoff, gbase, voff) do { _Pragma("unroll") for (int _i = 0; _i < 2; ++_i) \
;         __builtin_amdgcn_global_load_lds((const GAS unsigned*)((const GAS char*)(gbase) + (voff)[_i]), (LAS unsigned*)(lds + (bufoff) + ldsw + _i * 8192), 16, 0, 0); } while (0)
; #define PG8_LDA(dst, b, h) do { _Pragma("unroll") for (int m = 0; m < 4; ++m) _Pragma("unroll") for (int k = 0; k < 2; ++k) dst[m][k] = *(const LAS bf16x8*)(lds + PG8_SA(b, h) + aoff + m * 2048 + k * 1024); } while (0)
; #define PG8_LDB(dst, b, h) do { _Pragma("unroll") for (int n = 0; n < 2; ++n) _Pragma("unroll") for (int k = 0; k < 2; ++k) dst[n][k] = *(const LAS bf16x8*)(lds + PG8_SB(b, h) + boff + n * 2048 + k * 1024); } while (0)
; #define PG8_MMA(ai, bj, At, Bt) do { __builtin_amdgcn_sched_barrier(0); _Pragma("unroll") for (int m = 0; m < 4; ++m) _Pragma("unroll") for (int n = 0; n < 2; ++n) _Pragma("unroll") for (int k = 0; k < 2; ++k) \
;         acc[ai][bj][m][n] = __builtin_amdgcn_mfma_f32_16x16x32_bf16(Bt[n][k], At[m][k], acc[ai][bj][m][n], 0, 0, 0); __builtin_amdgcn_sched_barrier(0); } while (0)
; #define PG8_WAIT_V(n) asm volatile("s_waitcnt vmcnt(" #n ")" ::: "memory")
; #define PG8_WAIT_L(n) asm volatile("s_waitcnt lgkmcnt(" #n ")" ::: "memory")
; #define PG8_BAR __builtin_amdgcn_s_barrier()
; #define PG8_SCHED __builtin_amdgcn_sched_barrier(0)
; template <class Epi, class Sched, bool ALIGN_EPI, bool SP2>
; __device__ __forceinline__ void gemm_phase(LAS unsigned char* lds, const int tid, const Gemm g, const Sched& S, const Epi& E) {
;     ...
;             PG8_LDB(B0, 0, 0); PG8_LDB(B1, 0, 1); PG8_SCHED; PG8_LDA(At, 0, 0); PG8_STAGE(PG8_SA(1, 1), a1 + hstepA, voffA);
;             PG8_WAIT_V(8); PG8_WAIT_L(0); PG8_BAR; PG8_MMA(0, 0, At, B0); PG8_MMA(0, 1, At, B1); PG8_BAR; PG8_SCHED;
;             PG8_LDA(At, 0, 1); PG8_STAGE(PG8_SB(0, 0), b2, voffB); PG8_STAGE(PG8_SB(0, 1), b2 + hstepB, voffB); PG8_STAGE(PG8_SA(0, 0), a2, voffA);
;             PG8_WAIT_V(8); PG8_WAIT_L(0); PG8_BAR; PG8_MMA(1, 0, At, B0); PG8_MMA(1, 1, At, B1); PG8_BAR; PG8_SCHED;
.LBB0_463:
	s_add_u32 s40, s34, 0xfff80080
	s_addc_u32 s41, s35, -1
	s_add_i32 s63, 0, 0x10000
	s_cmp_eq_u32 s62, 28
	s_cselect_b32 s43, s23, s41
	s_cselect_b32 s42, s58, s40
	s_cselect_b32 s41, s19, s61
	s_cselect_b32 s40, s59, s60
	s_add_i32 s68, 0, 0x14000
	v_add_u32_e32 v142, s63, v160
	v_add_u32_e32 v163, s68, v160
	ds_read_b128 v[130:133], v142
	ds_read_b128 v[134:137], v142 offset:1024
	ds_read_b128 v[138:141], v142 offset:2048
	ds_read_b128 v[142:145], v142 offset:3072
	ds_read_b128 v[156:159], v163
	ds_read_b128 v[164:167], v163 offset:1024
	ds_read_b128 v[168:171], v163 offset:2048
	ds_read_b128 v[172:175], v163 offset:3072
	v_lshl_add_u64 v[200:201], s[34:35], 0, v[154:155]
	s_add_i32 m0, s48, 0xc000
	ds_read_b128 v[176:179], v162
	ds_read_b128 v[180:183], v162 offset:1024
	ds_read_b128 v[184:187], v162 offset:2048
	ds_read_b128 v[188:191], v162 offset:3072
	ds_read_b128 v[192:195], v162 offset:4096
	ds_read_b128 v[196:199], v162 offset:5120
	ds_read_b128 v[214:217], v162 offset:6144
	ds_read_b128 v[218:221], v162 offset:7168
	global_load_lds_dwordx4 v[200:201], off
	v_lshl_add_u64 v[200:201], s[34:35], 0, v[152:153]
	s_add_i32 m0, s48, 0xe000
	s_nop 0
	global_load_lds_dwordx4 v[200:201], off
	s_cmp_lg_u32 s100, 0
	s_cbranch_scc1 .Lp0_rw1
	s_waitcnt vmcnt(8)
.Lp0_rj1:
	s_waitcnt lgkmcnt(0)
	s_barrier
	s_waitcnt lgkmcnt(0)
	v_mfma_f32_16x16x32_bf16 v[126:129], v[130:133], v[176:179], v[126:129]
	v_mfma_f32_16x16x32_bf16 v[122:125], v[138:141], v[176:179], v[122:125]
	v_mfma_f32_16x16x32_bf16 v[114:117], v[130:133], v[184:187], v[114:117]
	v_mfma_f32_16x16x32_bf16 v[106:109], v[138:141], v[184:187], v[106:109]
	v_mfma_f32_16x16x32_bf16 v[98:101], v[130:133], v[192:195], v[98:101]
	v_mfma_f32_16x16x32_bf16 v[90:93], v[138:141], v[192:195], v[90:93]
	v_mfma_f32_16x16x32_bf16 v[82:85], v[130:133], v[214:217], v[82:85]
	v_mfma_f32_16x16x32_bf16 v[74:77], v[138:141], v[214:217], v[74:77]
	v_mfma_f32_16x16x32_bf16 v[126:129], v[134:137], v[180:183], v[126:129]
	v_mfma_f32_16x16x32_bf16 v[122:125], v[142:145], v[180:183], v[122:125]
	v_mfma_f32_16x16x32_bf16 v[114:117], v[134:137], v[188:191], v[114:117]
	v_mfma_f32_16x16x32_bf16 v[106:109], v[142:145], v[188:191], v[106:109]
	v_mfma_f32_16x16x32_bf16 v[98:101], v[134:137], v[196:199], v[98:101]
	v_mfma_f32_16x16x32_bf16 v[90:93], v[142:145], v[196:199], v[90:93]
	v_mfma_f32_16x16x32_bf16 v[82:85], v[134:137], v[218:221], v[82:85]
	v_mfma_f32_16x16x32_bf16 v[74:77], v[142:145], v[218:221], v[74:77]
	v_mfma_f32_16x16x32_bf16 v[118:121], v[156:159], v[176:179], v[118:121]
	v_mfma_f32_16x16x32_bf16 v[110:113], v[168:171], v[176:179], v[110:113]
	v_mfma_f32_16x16x32_bf16 v[102:105], v[156:159], v[184:187], v[102:105]
	v_mfma_f32_16x16x32_bf16 v[94:97], v[168:171], v[184:187], v[94:97]
	v_mfma_f32_16x16x32_bf16 v[86:89], v[156:159], v[192:195], v[86:89]
	v_mfma_f32_16x16x32_bf16 v[78:81], v[168:171], v[192:195], v[78:81]
	v_mfma_f32_16x16x32_bf16 v[70:73], v[156:159], v[214:217], v[70:73]
	v_mfma_f32_16x16x32_bf16 v[66:69], v[168:171], v[214:217], v[66:69]
	v_mfma_f32_16x16x32_bf16 v[118:121], v[164:167], v[180:183], v[118:121]
	v_mfma_f32_16x16x32_bf16 v[110:113], v[172:175], v[180:183], v[110:113]
	v_mfma_f32_16x16x32_bf16 v[102:105], v[164:167], v[188:191], v[102:105]
	v_mfma_f32_16x16x32_bf16 v[94:97], v[172:175], v[188:191], v[94:97]
	v_mfma_f32_16x16x32_bf16 v[86:89], v[164:167], v[196:199], v[86:89]
	v_mfma_f32_16x16x32_bf16 v[78:81], v[172:175], v[196:199], v[78:81]
	v_mfma_f32_16x16x32_bf16 v[70:73], v[164:167], v[218:221], v[70:73]
	v_mfma_f32_16x16x32_bf16 v[66:69], v[172:175], v[218:221], v[66:69]
	s_barrier
	s_add_i32 s63, s63, s47
	v_lshl_add_u64 v[200:201], s[40:41], 0, v[202:203]
	s_mov_b32 m0, s63
	ds_read_b128 v[176:179], v162 offset:16384
	ds_read_b128 v[180:183], v162 offset:17408
	ds_read_b128 v[184:187], v162 offset:18432
	ds_read_b128 v[188:191], v162 offset:19456
	ds_read_b128 v[192:195], v162 offset:20480
	ds_read_b128 v[196:199], v162 offset:21504
	ds_read_b128 v[214:217], v162 offset:22528
	ds_read_b128 v[218:221], v162 offset:23552
	global_load_lds_dwordx4 v[200:201], off
	s_add_i32 m0, s63, 0x2000
	s_add_u32 s64, s40, 0x80000
	v_lshl_add_u64 v[222:223], s[40:41], 0, v[150:151]
	s_addc_u32 s65, s41, 0
	s_add_i32 s63, s68, s47
	global_load_lds_dwordx4 v[222:223], off
	v_lshl_add_u64 v[224:225], s[64:65], 0, v[202:203]
	s_mov_b32 m0, s63
	v_lshl_add_u64 v[226:227], s[42:43], 0, v[148:149]
	global_load_lds_dwordx4 v[224:225], off
	v_lshl_add_u64 v[224:225], s[64:65], 0, v[150:151]
	s_add_i32 m0, s63, 0x2000
	s_nop 0
	global_load_lds_dwordx4 v[224:225], off
	v_lshl_add_u64 v[224:225], s[42:43], 0, v[146:147]
	s_mov_b32 m0, s48
	s_nop 0
	global_load_lds_dwordx4 v[224:225], off
	s_mov_b32 m0, s49
	s_nop 0
	global_load_lds_dwordx4 v[226:227], off
	s_cmp_lg_u32 s100, 0
	s_cbranch_scc1 .Lp0_rw2
	s_waitcnt vmcnt(8)
; #define PG8_STAGE(bufoff, gbase, voff) do { _Pragma("unroll") for (int _i = 0; _i < 2; ++_i) \
;         __builtin_amdgcn_global_load_lds((const GAS unsigned*)((const GAS char*)(gbase) + (voff)[_i]), (LAS unsigned*)(lds + (bufoff) + ldsw + _i * 8192), 16, 0, 0); } while (0)
; #define PG8_LDA(dst, b, h) do { _Pragma("unroll") for (int m = 0; m < 4; ++m) _Pragma("unroll") for (int k = 0; k < 2; ++k) dst[m][k] = *(const LAS bf16x8*)(lds + PG8_SA(b, h) + aoff + m * 2048 + k * 1024); } while (0)
; #define PG8_LDB(dst, b, h) do { _Pragma("unroll") for (int n = 0; n < 2; ++n) _Pragma("unroll") for (int k = 0; k < 2; ++k) dst[n][k] = *(const LAS bf16x8*)(lds + PG8_SB(b, h) + boff + n * 2048 + k * 1024); } while (0)
; #define PG8_MMA(ai, bj, At, Bt) do { __builtin_amdgcn_sched_barrier(0); _Pragma("unroll") for (int m = 0; m < 4; ++m) _Pragma("unroll") for (int n = 0; n < 2; ++n) _Pragma("unroll") for (int k = 0; k < 2; ++k) \
;         acc[ai][bj][m][n] = __builtin_amdgcn_mfma_f32_16x16x32_bf16(Bt[n][k], At[m][k], acc[ai][bj][m][n], 0, 0, 0); __builtin_amdgcn_sched_barrier(0); } while (0)
; #define PG8_WAIT_V(n) asm volatile("s_waitcnt vmcnt(" #n ")" ::: "memory")
; #define PG8_WAIT_L(n) asm volatile("s_waitcnt lgkmcnt(" #n ")" ::: "memory")
; #define PG8_BAR __builtin_amdgcn_s_barrier()
; #define PG8_SCHED __builtin_amdgcn_sched_barrier(0)
; template <class Epi, class Sched, bool ALIGN_EPI, bool SP2>
; __device__ __forceinline__ void gemm_phase(LAS unsigned char* lds, const int tid, const Gemm g, const Sched& S, const Epi& E) {
;     ...
;             PG8_WAIT_V(8); PG8_WAIT_L(0); PG8_BAR; PG8_MMA(1, 0, At, B0); PG8_MMA(1, 1, At, B1); PG8_BAR; PG8_SCHED;
;             PG8_LDB(B0, 1, 0); PG8_LDB(B1, 1, 1); PG8_SCHED; PG8_LDA(At, 1, 0); PG8_STAGE(PG8_SA(0, 1), a2 + hstepA, voffA);
;             PG8_WAIT_V(8); PG8_WAIT_L(0); PG8_BAR; PG8_MMA(0, 0, At, B0); PG8_MMA(0, 1, At, B1); PG8_BAR; PG8_SCHED;
.Lp0_rj2:
	s_mov_b32 s100, 0
	s_waitcnt lgkmcnt(0)
	s_barrier
	s_waitcnt lgkmcnt(0)
	v_mfma_f32_16x16x32_bf16 v[62:65], v[130:133], v[176:179], v[62:65]
	v_mfma_f32_16x16x32_bf16 v[58:61], v[138:141], v[176:179], v[58:61]
	v_mfma_f32_16x16x32_bf16 v[50:53], v[130:133], v[184:187], v[50:53]
	v_mfma_f32_16x16x32_bf16 v[42:45], v[138:141], v[184:187], v[42:45]
	v_mfma_f32_16x16x32_bf16 v[34:37], v[130:133], v[192:195], v[34:37]
	v_mfma_f32_16x16x32_bf16 v[26:29], v[138:141], v[192:195], v[26:29]
	v_mfma_f32_16x16x32_bf16 v[18:21], v[130:133], v[214:217], v[18:21]
	v_mfma_f32_16x16x32_bf16 v[10:13], v[138:141], v[214:217], v[10:13]
	v_mfma_f32_16x16x32_bf16 v[62:65], v[134:137], v[180:183], v[62:65]
	v_mfma_f32_16x16x32_bf16 v[58:61], v[142:145], v[180:183], v[58:61]
	v_mfma_f32_16x16x32_bf16 v[50:53], v[134:137], v[188:191], v[50:53]
	v_mfma_f32_16x16x32_bf16 v[42:45], v[142:145], v[188:191], v[42:45]
	v_mfma_f32_16x16x32_bf16 v[34:37], v[134:137], v[196:199], v[34:37]
	v_mfma_f32_16x16x32_bf16 v[26:29], v[142:145], v[196:199], v[26:29]
	v_mfma_f32_16x16x32_bf16 v[18:21], v[134:137], v[218:221], v[18:21]
	v_mfma_f32_16x16x32_bf16 v[10:13], v[142:145], v[218:221], v[10:13]
	v_mfma_f32_16x16x32_bf16 v[54:57], v[156:159], v[176:179], v[54:57]
	v_mfma_f32_16x16x32_bf16 v[46:49], v[168:171], v[176:179], v[46:49]
	v_mfma_f32_16x16x32_bf16 v[38:41], v[156:159], v[184:187], v[38:41]
	v_mfma_f32_16x16x32_bf16 v[30:33], v[168:171], v[184:187], v[30:33]
	v_mfma_f32_16x16x32_bf16 v[22:25], v[156:159], v[192:195], v[22:25]
	v_mfma_f32_16x16x32_bf16 v[14:17], v[168:171], v[192:195], v[14:17]
	v_mfma_f32_16x16x32_bf16 v[6:9], v[156:159], v[214:217], v[6:9]
	v_mfma_f32_16x16x32_bf16 v[2:5], v[168:171], v[214:217], v[2:5]
	v_mfma_f32_16x16x32_bf16 v[54:57], v[164:167], v[180:183], v[54:57]
	v_mfma_f32_16x16x32_bf16 v[46:49], v[172:175], v[180:183], v[46:49]
	v_mfma_f32_16x16x32_bf16 v[38:41], v[164:167], v[188:191], v[38:41]
	v_mfma_f32_16x16x32_bf16 v[30:33], v[172:175], v[188:191], v[30:33]
	v_mfma_f32_16x16x32_bf16 v[22:25], v[164:167], v[196:199], v[22:25]
	v_mfma_f32_16x16x32_bf16 v[14:17], v[172:175], v[196:199], v[14:17]
	v_mfma_f32_16x16x32_bf16 v[6:9], v[164:167], v[218:221], v[6:9]
	v_mfma_f32_16x16x32_bf16 v[2:5], v[172:175], v[218:221], v[2:5]
	s_barrier
	s_add_i32 s63, 0, 0x18000
	s_add_i32 s64, 0, 0x1c000
	v_add_u32_e32 v142, s63, v160
	v_add_u32_e32 v163, s64, v160
	ds_read_b128 v[130:133], v142
	ds_read_b128 v[134:137], v142 offset:1024
	ds_read_b128 v[138:141], v142 offset:2048
	ds_read_b128 v[142:145], v142 offset:3072
	ds_read_b128 v[156:159], v163
	ds_read_b128 v[164:167], v163 offset:1024
	ds_read_b128 v[168:171], v163 offset:2048
	ds_read_b128 v[172:175], v163 offset:3072
	s_add_u32 s42, s42, 0x80000
	s_addc_u32 s43, s43, 0
	s_mov_b32 m0, s50
	v_lshl_add_u64 v[246:247], s[42:43], 0, v[146:147]
	ds_read_b128 v[176:179], v162 offset:32768
	ds_read_b128 v[180:183], v162 offset:33792
	ds_read_b128 v[184:187], v162 offset:34816
	ds_read_b128 v[188:191], v162 offset:35840
	ds_read_b128 v[192:195], v162 offset:36864
	ds_read_b128 v[196:199], v162 offset:37888
	ds_read_b128 v[214:217], v162 offset:38912
	ds_read_b128 v[218:221], v162 offset:39936
	global_load_lds_dwordx4 v[246:247], off
	v_lshl_add_u64 v[246:247], s[42:43], 0, v[148:149]
	s_mov_b32 m0, s51
	s_nop 0
	global_load_lds_dwordx4 v[246:247], off
	s_waitcnt vmcnt(8)
	s_waitcnt lgkmcnt(0)
	s_barrier
	s_waitcnt lgkmcnt(0)
	v_mfma_f32_16x16x32_bf16 v[126:129], v[130:133], v[176:179], v[126:129]
	v_mfma_f32_16x16x32_bf16 v[122:125], v[138:141], v[176:179], v[122:125]
	v_mfma_f32_16x16x32_bf16 v[114:117], v[130:133], v[184:187], v[114:117]
	v_mfma_f32_16x16x32_bf16 v[106:109], v[138:141], v[184:187], v[106:109]
	v_mfma_f32_16x16x32_bf16 v[98:101], v[130:133], v[192:195], v[98:101]
	v_mfma_f32_16x16x32_bf16 v[90:93], v[138:141], v[192:195], v[90:93]
	v_mfma_f32_16x16x32_bf16 v[82:85], v[130:133], v[214:217], v[82:85]
	v_mfma_f32_16x16x32_bf16 v[74:77], v[138:141], v[214:217], v[74:77]
	v_mfma_f32_16x16x32_bf16 v[126:129], v[134:137], v[180:183], v[126:129]
	v_mfma_f32_16x16x32_bf16 v[122:125], v[142:145], v[180:183], v[122:125]
	v_mfma_f32_16x16x32_bf16 v[114:117], v[134:137], v[188:191], v[114:117]
	v_mfma_f32_16x16x32_bf16 v[106:109], v[142:145], v[188:191], v[106:109]
	v_mfma_f32_16x16x32_bf16 v[98:101], v[134:137], v[196:199], v[98:101]
	v_mfma_f32_16x16x32_bf16 v[90:93], v[142:145], v[196:199], v[90:93]
	v_mfma_f32_16x16x32_bf16 v[82:85], v[134:137], v[218:221], v[82:85]
	v_mfma_f32_16x16x32_bf16 v[74:77], v[142:145], v[218:221], v[74:77]
	v_mfma_f32_16x16x32_bf16 v[118:121], v[156:159], v[176:179], v[118:121]
	v_mfma_f32_16x16x32_bf16 v[110:113], v[168:171], v[176:179], v[110:113]
	v_mfma_f32_16x16x32_bf16 v[102:105], v[156:159], v[184:187], v[102:105]
	v_mfma_f32_16x16x32_bf16 v[94:97], v[168:171], v[184:187], v[94:97]
	v_mfma_f32_16x16x32_bf16 v[86:89], v[156:159], v[192:195], v[86:89]
	v_mfma_f32_16x16x32_bf16 v[78:81], v[168:171], v[192:195], v[78:81]
	v_mfma_f32_16x16x32_bf16 v[70:73], v[156:159], v[214:217], v[70:73]
	v_mfma_f32_16x16x32_bf16 v[66:69], v[168:171], v[214:217], v[66:69]
	v_mfma_f32_16x16x32_bf16 v[118:121], v[164:167], v[180:183], v[118:121]
	v_mfma_f32_16x16x32_bf16 v[110:113], v[172:175], v[180:183], v[110:113]
	v_mfma_f32_16x16x32_bf16 v[102:105], v[164:167], v[188:191], v[102:105]
	v_mfma_f32_16x16x32_bf16 v[94:97], v[172:175], v[188:191], v[94:97]
	v_mfma_f32_16x16x32_bf16 v[86:89], v[164:167], v[196:199], v[86:89]
	v_mfma_f32_16x16x32_bf16 v[78:81], v[172:175], v[196:199], v[78:81]
	v_mfma_f32_16x16x32_bf16 v[70:73], v[164:167], v[218:221], v[70:73]
	v_mfma_f32_16x16x32_bf16 v[66:69], v[172:175], v[218:221], v[66:69]
	s_barrier
; #define PG8_STAGE(bufoff, gbase, voff) do { _Pragma("unroll") for (int _i = 0; _i < 2; ++_i) \
;         __builtin_amdgcn_global_load_lds((const GAS unsigned*)((const GAS char*)(gbase) + (voff)[_i]), (LAS unsigned*)(lds + (bufoff) + ldsw + _i * 8192), 16, 0, 0); } while (0)
; #define PG8_LDA(dst, b, h) do { _Pragma("unroll") for (int m = 0; m < 4; ++m) _Pragma("unroll") for (int k = 0; k < 2; ++k) dst[m][k] = *(const LAS bf16x8*)(lds + PG8_SA(b, h) + aoff + m * 2048 + k * 1024); } while (0)
; #define PG8_MMA(ai, bj, At, Bt) do { __builtin_amdgcn_sched_barrier(0); _Pragma("unroll") for (int m = 0; m < 4; ++m) _Pragma("unroll") for (int n = 0; n < 2; ++n) _Pragma("unroll") for (int k = 0; k < 2; ++k) \
;         acc[ai][bj][m][n] = __builtin_amdgcn_mfma_f32_16x16x32_bf16(Bt[n][k], At[m][k], acc[ai][bj][m][n], 0, 0, 0); __builtin_amdgcn_sched_barrier(0); } while (0)
; #define PG8_WAIT_V(n) asm volatile("s_waitcnt vmcnt(" #n ")" ::: "memory")
; #define PG8_WAIT_L(n) asm volatile("s_waitcnt lgkmcnt(" #n ")" ::: "memory")
; #define PG8_BAR __builtin_amdgcn_s_barrier()
; #define PG8_SCHED __builtin_amdgcn_sched_barrier(0)
; template <class Epi, class Sched, bool ALIGN_EPI, bool SP2>
; __device__ __forceinline__ void gemm_phase(LAS unsigned char* lds, const int tid, const Gemm g, const Sched& S, const Epi& E) {
;     ...
;             PG8_LDA(At, 1, 1); PG8_STAGE(PG8_SB(1, 0), b3, voffB); PG8_STAGE(PG8_SB(1, 1), b3 + hstepB, voffB); PG8_STAGE(PG8_SA(1, 0), a3, voffA);
;             PG8_WAIT_V(8); PG8_WAIT_L(0); PG8_BAR; PG8_MMA(1, 0, At, B0); PG8_MMA(1, 1, At, B1); PG8_BAR; PG8_SCHED;
	s_add_i32 s42, s63, s47
	v_lshl_add_u64 v[200:201], v[200:201], 0, s[14:15]
	s_mov_b32 m0, s42
	ds_read_b128 v[176:179], v162 offset:49152
	ds_read_b128 v[180:183], v162 offset:50176
	ds_read_b128 v[184:187], v162 offset:51200
	ds_read_b128 v[188:191], v162 offset:52224
	ds_read_b128 v[192:195], v162 offset:53248
	ds_read_b128 v[196:199], v162 offset:54272
	ds_read_b128 v[214:217], v162 offset:55296
	ds_read_b128 v[218:221], v162 offset:56320
	global_load_lds_dwordx4 v[200:201], off
	s_add_i32 m0, s42, 0x2000
	s_add_u32 s40, s40, 0x80080
	v_lshl_add_u64 v[200:201], v[222:223], 0, s[14:15]
	s_addc_u32 s41, s41, 0
	s_add_i32 s42, s64, s47
	global_load_lds_dwordx4 v[200:201], off
	v_lshl_add_u64 v[200:201], s[40:41], 0, v[202:203]
	s_mov_b32 m0, s42
	s_nop 0
	global_load_lds_dwordx4 v[200:201], off
	v_lshl_add_u64 v[200:201], s[40:41], 0, v[150:151]
	s_add_i32 m0, s42, 0x2000
	s_nop 0
	global_load_lds_dwordx4 v[200:201], off
	v_lshl_add_u64 v[200:201], v[224:225], 0, s[14:15]
	s_mov_b32 m0, s52
	s_nop 0
	global_load_lds_dwordx4 v[200:201], off
	v_lshl_add_u64 v[200:201], v[226:227], 0, s[14:15]
	s_mov_b32 m0, s53
	s_nop 0
	global_load_lds_dwordx4 v[200:201], off
	s_waitcnt vmcnt(8)
	s_waitcnt lgkmcnt(0)
	s_barrier
	s_waitcnt lgkmcnt(0)
	v_mfma_f32_16x16x32_bf16 v[62:65], v[130:133], v[176:179], v[62:65]
	v_mfma_f32_16x16x32_bf16 v[58:61], v[138:141], v[176:179], v[58:61]
	v_mfma_f32_16x16x32_bf16 v[50:53], v[130:133], v[184:187], v[50:53]
	v_mfma_f32_16x16x32_bf16 v[42:45], v[138:141], v[184:187], v[42:45]
	v_mfma_f32_16x16x32_bf16 v[34:37], v[130:133], v[192:195], v[34:37]
	v_mfma_f32_16x16x32_bf16 v[26:29], v[138:141], v[192:195], v[26:29]
	v_mfma_f32_16x16x32_bf16 v[18:21], v[130:133], v[214:217], v[18:21]
	v_mfma_f32_16x16x32_bf16 v[10:13], v[138:141], v[214:217], v[10:13]
	v_mfma_f32_16x16x32_bf16 v[62:65], v[134:137], v[180:183], v[62:65]
	v_mfma_f32_16x16x32_bf16 v[58:61], v[142:145], v[180:183], v[58:61]
	v_mfma_f32_16x16x32_bf16 v[50:53], v[134:137], v[188:191], v[50:53]
	v_mfma_f32_16x16x32_bf16 v[42:45], v[142:145], v[188:191], v[42:45]
	v_mfma_f32_16x16x32_bf16 v[34:37], v[134:137], v[196:199], v[34:37]
	v_mfma_f32_16x16x32_bf16 v[26:29], v[142:145], v[196:199], v[26:29]
	v_mfma_f32_16x16x32_bf16 v[18:21], v[134:137], v[218:221], v[18:21]
	v_mfma_f32_16x16x32_bf16 v[10:13], v[142:145], v[218:221], v[10:13]
	v_mfma_f32_16x16x32_bf16 v[54:57], v[156:159], v[176:179], v[54:57]
	v_mfma_f32_16x16x32_bf16 v[46:49], v[168:171], v[176:179], v[46:49]
	v_mfma_f32_16x16x32_bf16 v[38:41], v[156:159], v[184:187], v[38:41]
	v_mfma_f32_16x16x32_bf16 v[30:33], v[168:171], v[184:187], v[30:33]
	v_mfma_f32_16x16x32_bf16 v[22:25], v[156:159], v[192:195], v[22:25]
	v_mfma_f32_16x16x32_bf16 v[14:17], v[168:171], v[192:195], v[14:17]
	v_mfma_f32_16x16x32_bf16 v[6:9], v[156:159], v[214:217], v[6:9]
	v_mfma_f32_16x16x32_bf16 v[2:5], v[168:171], v[214:217], v[2:5]
	v_mfma_f32_16x16x32_bf16 v[54:57], v[164:167], v[180:183], v[54:57]
	v_mfma_f32_16x16x32_bf16 v[46:49], v[172:175], v[180:183], v[46:49]
	v_mfma_f32_16x16x32_bf16 v[38:41], v[164:167], v[188:191], v[38:41]
	v_mfma_f32_16x16x32_bf16 v[30:33], v[172:175], v[188:191], v[30:33]
	v_mfma_f32_16x16x32_bf16 v[22:25], v[164:167], v[196:199], v[22:25]
	v_mfma_f32_16x16x32_bf16 v[14:17], v[172:175], v[196:199], v[14:17]
	v_mfma_f32_16x16x32_bf16 v[6:9], v[164:167], v[218:221], v[6:9]
	v_mfma_f32_16x16x32_bf16 v[2:5], v[172:175], v[218:221], v[2:5]
	s_barrier
	s_add_i32 s62, s62, 2
	s_add_u32 s60, s60, 0x100
	s_addc_u32 s61, s61, 0
	s_add_u32 s34, s34, 0x100
	s_addc_u32 s35, s35, 0
	s_cmp_gt_u32 s62, 29
	s_cbranch_scc0 .LBB0_463
	v_lshl_or_b32 v158, s56, 8, v161
	v_ashrrev_i32_e32 v159, 31, v158
	s_branch .LBB0_459
.Lp0_rw1:
	s_waitcnt vmcnt(28)
	s_branch .Lp0_rj1

; #define GAS __attribute__((address_space(1)))
; #define PG8_STAGE(bufoff, gbase, voff) do { _Pragma("unroll") for (int _i = 0; _i < 2; ++_i) \
;         __builtin_amdgcn_global_load_lds((const GAS unsigned*)((const GAS char*)(gbase) + (voff)[_i]), (LAS unsigned*)(lds + (bufoff) + ldsw + _i * 8192), 16, 0, 0); } while (0)
; #define PG8_WAIT_V(n) asm volatile("s_waitcnt vmcnt(" #n ")" ::: "memory")
; #define PG8_BAR __builtin_amdgcn_s_barrier()
; template <class Epi, class Sched, bool ALIGN_EPI, bool SP2>
; __device__ __forceinline__ void gemm_phase(LAS unsigned char* lds, const int tid, const Gemm g, const Sched& S, const Epi& E) {
;     const int wid = __builtin_amdgcn_readfirstlane(tid >> 6), lane = tid & 63, wr = wid >> 2, wc = wid & 3, fr = lane & 15, fq = lane >> 4;
;     const int nt0 = g.K / BK;
;     unsigned voffA[2], voffB[2];
; #pragma unroll
;     for (int i = 0; i < 2; ++i) { int R, C; stage_rc(tid * 16 + i * 8192, R, C); const int Rb = Epi::PERM ? ((R & ~31) + perm32(R & 31)) : R;
;         voffA[i] = (unsigned)(R * g.lda + C) * 2u; voffB[i] = (unsigned)(Rb * g.ldb + C) * 2u; }
;     const size_t kstep = (size_t)(BK * 2);
;     const size_t hstepA = (size_t)HALF * g.lda * 2, hstepB = (size_t)HALF * g.ldb * 2;
;     const unsigned ldsw = (unsigned)wid * 1024u;
;     const int aoff = lds_byte(wr * 64 + fr, fq * 8), boff = lds_byte(wc * 32 + fr, fq * 8);
;     ...
;     Unit cur, nxt; int ui = 0;
;     if (!S.next(0, cur)) return;
;     if (wr == 1) __builtin_amdgcn_s_setprio(1);
;     f32x4 acc[2][2][4][2];
; #pragma unroll
;     for (int a = 0; a < 2; ++a)
; #pragma unroll
;         for (int b = 0; b < 2; ++b)
; #pragma unroll
;             for (int m = 0; m < 4; ++m)
; #pragma unroll
;                 for (int n = 0; n < 2; ++n) acc[a][b][m][n] = (f32x4){0.f, 0.f, 0.f, 0.f};
;     bf16x8 At[4][2], B0[2][2], B1[2][2];
;     const GAS char* cA = S.aptr(cur); const GAS char* cB = S.bptr(cur);
;     if constexpr (SP2) {
;         PG8_STAGE(PG8_SB(0, 0), cB, voffB); PG8_STAGE(PG8_SB(0, 1), cB + hstepB, voffB); PG8_STAGE(PG8_SA(0, 0), cA, voffA); PG8_STAGE(PG8_SA(0, 1), cA + hstepA, voffA);
;         if (wr == 1) PG8_BAR;
;         PG8_WAIT_V(2); PG8_BAR;
;         PG8_STAGE(PG8_SB(1, 0), cB + kstep, voffB); PG8_STAGE(PG8_SA(1, 0), cA + kstep, voffA); PG8_STAGE(PG8_SB(1, 1), cB + hstepB + kstep, voffB);
;         PG8_WAIT_V(6); PG8_BAR;
.LBB0_739:
	s_waitcnt vmcnt(0)
	v_lshrrev_b32_e32 v11, 1, v0
	v_and_b32_e32 v11, 24, v11
	v_and_b32_e32 v1, 15, v0
	v_lshlrev_b32_e32 v12, 1, v11
	v_lshl_or_b32 v10, s11, 6, v1
	v_lshl_or_b32 v1, v1, 6, v12
	v_lshlrev_b32_e32 v12, 2, v0
	s_lshl_b32 s6, s11, 13
	v_and_b32_e32 v12, 32, v12
	v_lshl_add_u64 v[2:3], s[18:19], 0, v[202:203]
	v_mov_b32_e32 v135, v203
	v_bitop3_b32 v13, v1, s6, v12 bitop3:0xde
	s_lshl_b32 s6, s12, 5
	v_lshl_add_u64 v[4:5], s[18:19], 0, v[134:135]
	v_mov_b32_e32 v131, v203
	s_and_b32 s8, s6, 0x60
	s_add_i32 m0, s55, 0x18000
	v_lshl_add_u64 v[2:3], v[2:3], 0, s[14:15]
	v_lshl_add_u64 v[6:7], s[22:23], 0, v[130:131]
	v_mov_b32_e32 v133, v203
	s_lshl_b32 s6, s8, 7
	s_waitcnt vmcnt(2)
	s_barrier
	global_load_lds_dwordx4 v[2:3], off
	v_lshl_add_u64 v[2:3], v[4:5], 0, s[14:15]
	s_add_i32 m0, s55, 0x1a000
	s_add_i32 s63, s55, 0x8000
	s_add_i32 s64, s55, 0xa000
	v_lshl_add_u64 v[8:9], s[22:23], 0, v[132:133]
	v_bitop3_b32 v1, s6, v1, v12 bitop3:0xf6
	global_load_lds_dwordx4 v[2:3], off
	v_lshl_add_u64 v[2:3], v[6:7], 0, s[14:15]
	s_mov_b32 m0, s63
	s_add_u32 s6, s18, 0x10080
	global_load_lds_dwordx4 v[2:3], off
	v_lshl_add_u64 v[2:3], v[8:9], 0, s[14:15]
	s_mov_b32 m0, s64
	s_addc_u32 s7, s19, 0
	global_load_lds_dwordx4 v[2:3], off
	s_add_i32 m0, s55, 0x1c000
	v_lshl_add_u64 v[2:3], s[6:7], 0, v[202:203]
	global_load_lds_dwordx4 v[2:3], off
	v_lshl_add_u64 v[2:3], s[6:7], 0, v[134:135]
	s_add_i32 m0, s55, 0x1e000
	s_cmpk_lt_u32 s10, 0x100
	global_load_lds_dwordx4 v[2:3], off
	v_mul_lo_u32 v2, v10, s24
	s_waitcnt vmcnt(6)
	v_or3_b32 v2, v11, s8, v2
	v_add_u32_e32 v137, 0x100, v2
	v_mov_b32_e32 v2, 0
	v_readlane_b32 s8, v254, 23
	s_cselect_b64 s[6:7], -1, 0
	s_mov_b32 s70, 0
	v_add_u32_e32 v140, 0, v13
	s_mov_b32 s56, s8
	v_readlane_b32 s71, v254, 21
	s_mov_b32 s69, 0
	v_mov_b32_e32 v3, v2
	v_mov_b32_e32 v4, v2
	v_mov_b32_e32 v5, v2
	v_mov_b32_e32 v6, v2
	v_mov_b32_e32 v7, v2
	v_mov_b32_e32 v8, v2
	v_mov_b32_e32 v9, v2
	v_mov_b32_e32 v10, v2
	v_mov_b32_e32 v11, v2
	v_mov_b32_e32 v12, v2
	v_mov_b32_e32 v13, v2
	v_mov_b32_e32 v14, v2
	v_mov_b32_e32 v15, v2
	v_mov_b32_e32 v16, v2
	v_mov_b32_e32 v17, v2
	v_mov_b32_e32 v18, v2
	v_mov_b32_e32 v19, v2
	v_mov_b32_e32 v20, v2
	v_mov_b32_e32 v21, v2
	v_mov_b32_e32 v22, v2
	v_mov_b32_e32 v23, v2
	v_mov_b32_e32 v24, v2
	v_mov_b32_e32 v25, v2
	v_mov_b32_e32 v26, v2
	v_mov_b32_e32 v27, v2
	v_mov_b32_e32 v28, v2
	v_mov_b32_e32 v29, v2
	v_mov_b32_e32 v30, v2
	v_mov_b32_e32 v31, v2
	v_mov_b32_e32 v32, v2
	v_mov_b32_e32 v33, v2
	v_mov_b32_e32 v34, v2
	v_mov_b32_e32 v35, v2
	v_mov_b32_e32 v36, v2
	v_mov_b32_e32 v37, v2
	v_mov_b32_e32 v38, v2
	v_mov_b32_e32 v39, v2
	v_mov_b32_e32 v40, v2
	v_mov_b32_e32 v41, v2
	v_mov_b32_e32 v42, v2
	v_mov_b32_e32 v43, v2
	v_mov_b32_e32 v44, v2
	v_mov_b32_e32 v45, v2
	v_mov_b32_e32 v46, v2
	v_mov_b32_e32 v47, v2
	v_mov_b32_e32 v48, v2
	v_mov_b32_e32 v49, v2
	v_mov_b32_e32 v50, v2
	v_mov_b32_e32 v51, v2
	v_mov_b32_e32 v52, v2
	v_mov_b32_e32 v53, v2
	v_mov_b32_e32 v54, v2
	v_mov_b32_e32 v55, v2
	v_mov_b32_e32 v56, v2
	v_mov_b32_e32 v57, v2
	v_mov_b32_e32 v58, v2
	v_mov_b32_e32 v59, v2
	v_mov_b32_e32 v60, v2
	v_mov_b32_e32 v61, v2
	v_mov_b32_e32 v62, v2
	v_mov_b32_e32 v63, v2
	v_mov_b32_e32 v64, v2
	v_mov_b32_e32 v65, v2
	v_mov_b32_e32 v66, v2
	v_mov_b32_e32 v67, v2
	v_mov_b32_e32 v68, v2
	v_mov_b32_e32 v69, v2
	v_mov_b32_e32 v70, v2
	v_mov_b32_e32 v71, v2
	v_mov_b32_e32 v72, v2
	v_mov_b32_e32 v73, v2
	v_mov_b32_e32 v74, v2
	v_mov_b32_e32 v75, v2
	v_mov_b32_e32 v76, v2
	v_mov_b32_e32 v77, v2
	v_mov_b32_e32 v78, v2
	v_mov_b32_e32 v79, v2
	v_mov_b32_e32 v80, v2
	v_mov_b32_e32 v81, v2
	v_mov_b32_e32 v82, v2
	v_mov_b32_e32 v83, v2
	v_mov_b32_e32 v84, v2
	v_mov_b32_e32 v85, v2
	v_mov_b32_e32 v86, v2
	v_mov_b32_e32 v87, v2
	v_mov_b32_e32 v88, v2
	v_mov_b32_e32 v89, v2
	v_mov_b32_e32 v90, v2
	v_mov_b32_e32 v91, v2
	v_mov_b32_e32 v92, v2
	v_mov_b32_e32 v93, v2
	v_mov_b32_e32 v94, v2
	v_mov_b32_e32 v95, v2
	v_mov_b32_e32 v96, v2
	v_mov_b32_e32 v97, v2
	v_mov_b32_e32 v98, v2
	v_mov_b32_e32 v99, v2
	v_mov_b32_e32 v100, v2
	v_mov_b32_e32 v101, v2
	v_mov_b32_e32 v102, v2
	v_mov_b32_e32 v103, v2
	v_mov_b32_e32 v104, v2
	v_mov_b32_e32 v105, v2
	v_mov_b32_e32 v106, v2
	v_mov_b32_e32 v107, v2
	v_mov_b32_e32 v108, v2
	v_mov_b32_e32 v109, v2
	v_mov_b32_e32 v110, v2
	v_mov_b32_e32 v111, v2
	v_mov_b32_e32 v112, v2
	v_mov_b32_e32 v113, v2
	v_mov_b32_e32 v114, v2
	v_mov_b32_e32 v115, v2
	v_mov_b32_e32 v116, v2
	v_mov_b32_e32 v117, v2
	v_mov_b32_e32 v118, v2
	v_mov_b32_e32 v119, v2
	v_mov_b32_e32 v120, v2
	v_mov_b32_e32 v121, v2
	v_mov_b32_e32 v122, v2
	v_mov_b32_e32 v123, v2
	v_mov_b32_e32 v124, v2
	v_mov_b32_e32 v125, v2
	v_mov_b32_e32 v126, v2
	v_mov_b32_e32 v127, v2
	v_mov_b32_e32 v128, v2
	v_mov_b32_e32 v129, v2
	s_barrier
	v_readlane_b32 s9, v254, 24
	s_mov_b32 s100, 0
	s_branch .LBB0_743

; #define GAS __attribute__((address_space(1)))
; #define PG8_STAGE(bufoff, gbase, voff) do { _Pragma("unroll") for (int _i = 0; _i < 2; ++_i) \
;         __builtin_amdgcn_global_load_lds((const GAS unsigned*)((const GAS char*)(gbase) + (voff)[_i]), (LAS unsigned*)(lds + (bufoff) + ldsw + _i * 8192), 16, 0, 0); } while (0)
; #define PG8_LDA(dst, b, h) do { _Pragma("unroll") for (int m = 0; m < 4; ++m) _Pragma("unroll") for (int k = 0; k < 2; ++k) dst[m][k] = *(const LAS bf16x8*)(lds + PG8_SA(b, h) + aoff + m * 2048 + k * 1024); } while (0)
; #define PG8_LDB(dst, b, h) do { _Pragma("unroll") for (int n = 0; n < 2; ++n) _Pragma("unroll") for (int k = 0; k < 2; ++k) dst[n][k] = *(const LAS bf16x8*)(lds + PG8_SB(b, h) + boff + n * 2048 + k * 1024); } while (0)
; #define PG8_MMA(ai, bj, At, Bt) do { __builtin_amdgcn_sched_barrier(0); _Pragma("unroll") for (int m = 0; m < 4; ++m) _Pragma("unroll") for (int n = 0; n < 2; ++n) _Pragma("unroll") for (int k = 0; k < 2; ++k) \
;         acc[ai][bj][m][n] = __builtin_amdgcn_mfma_f32_16x16x32_bf16(Bt[n][k], At[m][k], acc[ai][bj][m][n], 0, 0, 0); __builtin_amdgcn_sched_barrier(0); } while (0)
; #define PG8_WAIT_V(n) asm volatile("s_waitcnt vmcnt(" #n ")" ::: "memory")
; #define PG8_BAR __builtin_amdgcn_s_barrier()
; template <class Epi, class Sched, bool ALIGN_EPI, bool SP2>
; __device__ __forceinline__ void gemm_phase(LAS unsigned char* lds, const int tid, const Gemm g, const Sched& S, const Epi& E) {
;     ...
;         for (int t = 0; t < nt; t += 2) {
;             const bool last = (t == nt - 2);
;             const GAS char* a1 = cA + (size_t)(t + 1) * kstep;
;             const GAS char* a2 = last ? nA : cA + (size_t)(t + 2) * kstep; const GAS char* b2 = last ? nB : cB + (size_t)(t + 2) * kstep;
;             const GAS char* a3 = a2 + kstep; const GAS char* b3 = b2 + kstep;
;             if constexpr (SP2) {
;             PG8_LDB(B0, 0, 0); PG8_LDB(B1, 0, 1); PG8_SCHED; PG8_LDA(At, 0, 0); PG8_STAGE(PG8_SA(1, 1), a1 + hstepA, voffA);
;             PG8_WAIT_V(8); PG8_WAIT_L(0); PG8_BAR; PG8_MMA(0, 0, At, B0); PG8_MMA(0, 1, At, B1); PG8_BAR; PG8_SCHED;
;             PG8_LDA(At, 0, 1); PG8_STAGE(PG8_SB(0, 0), b2, voffB); PG8_STAGE(PG8_SB(0, 1), b2 + hstepB, voffB); PG8_STAGE(PG8_SA(0, 0), a2, voffA);
;             PG8_WAIT_V(8); PG8_WAIT_L(0); PG8_BAR; PG8_MMA(1, 0, At, B0); PG8_MMA(1, 1, At, B1); PG8_BAR; PG8_SCHED;
.LBB0_748:
	s_add_u32 s46, s22, s34
	s_addc_u32 s47, s23, s35
	s_add_u32 s44, s46, 0x100
	s_addc_u32 s45, s47, 0
	s_and_b64 s[42:43], s[26:27], exec
	s_cselect_b32 s43, s11, s45
	s_cselect_b32 s42, s10, s44
	s_add_u32 s34, s18, s34
	s_addc_u32 s35, s19, s35
	s_add_u32 s34, s34, 0x100
	s_addc_u32 s35, s35, 0
	s_add_i32 s86, 0, 0x10000
	s_and_b64 s[26:27], s[26:27], exec
	s_cselect_b32 s45, s9, s35
	s_cselect_b32 s44, s58, s34
	s_add_i32 s27, 0, 0x14000
	s_add_u32 s50, s46, 0x30080
	s_addc_u32 s51, s47, 0
	s_add_i32 s93, s86, s4
	s_add_i32 m0, s55, 0xc000
	s_add_i32 s87, s55, 0xe000
	s_add_i32 s85, s93, 0x2000
	v_add_u32_e32 v136, s86, v1
	s_add_u32 s46, s44, 0x10000
	ds_read_b128 v[142:145], v136
	ds_read_b128 v[146:149], v136 offset:1024
	ds_read_b128 v[150:153], v136 offset:2048
	ds_read_b128 v[154:157], v136 offset:3072
	v_add_u32_e32 v136, s27, v1
	s_addc_u32 s47, s45, 0
	s_add_i32 s92, s27, s4
	ds_read_b128 v[158:161], v136
	ds_read_b128 v[162:165], v136 offset:1024
	ds_read_b128 v[166:169], v136 offset:2048
	ds_read_b128 v[170:173], v136 offset:3072
	s_add_i32 s91, s92, 0x2000
	s_add_i32 s82, 0, 0x18000
	s_add_i32 s73, 0, 0x1c000
	s_add_u32 s34, s42, 0x30000
	s_addc_u32 s35, s43, 0
	s_add_i32 s72, s82, s4
	s_add_i32 s59, s72, 0x2000
	s_add_u32 s26, s44, 0x10080
	s_addc_u32 s27, s45, 0
	s_add_i32 s95, s73, s4
	s_add_i32 s94, s95, 0x2000
	v_lshl_add_u64 v[138:139], s[50:51], 0, v[130:131]
	ds_read_b128 v[174:177], v140
	ds_read_b128 v[178:181], v140 offset:1024
	ds_read_b128 v[182:185], v140 offset:2048
	ds_read_b128 v[186:189], v140 offset:3072
	ds_read_b128 v[190:193], v140 offset:4096
	ds_read_b128 v[194:197], v140 offset:5120
	ds_read_b128 v[198:201], v140 offset:6144
	ds_read_b128 v[214:217], v140 offset:7168
	global_load_lds_dwordx4 v[138:139], off
	v_lshl_add_u64 v[138:139], s[50:51], 0, v[132:133]
	s_mov_b32 m0, s87
	s_nop 0
	global_load_lds_dwordx4 v[138:139], off
	s_cmp_lg_u32 s100, 0
	s_cbranch_scc1 .Lch_rw1
	s_waitcnt vmcnt(8)
.Lch_rj1:
	s_waitcnt lgkmcnt(0)
	s_barrier
	s_waitcnt lgkmcnt(0)
	v_mfma_f32_16x16x32_bf16 v[126:129], v[142:145], v[174:177], v[126:129]
	v_mfma_f32_16x16x32_bf16 v[122:125], v[150:153], v[174:177], v[122:125]
	v_mfma_f32_16x16x32_bf16 v[118:121], v[142:145], v[182:185], v[118:121]
	v_mfma_f32_16x16x32_bf16 v[114:117], v[150:153], v[182:185], v[114:117]
	v_mfma_f32_16x16x32_bf16 v[110:113], v[142:145], v[190:193], v[110:113]
	v_mfma_f32_16x16x32_bf16 v[106:109], v[150:153], v[190:193], v[106:109]
	v_mfma_f32_16x16x32_bf16 v[102:105], v[142:145], v[198:201], v[102:105]
	v_mfma_f32_16x16x32_bf16 v[98:101], v[150:153], v[198:201], v[98:101]
	v_mfma_f32_16x16x32_bf16 v[126:129], v[146:149], v[178:181], v[126:129]
	v_mfma_f32_16x16x32_bf16 v[122:125], v[154:157], v[178:181], v[122:125]
	v_mfma_f32_16x16x32_bf16 v[118:121], v[146:149], v[186:189], v[118:121]
	v_mfma_f32_16x16x32_bf16 v[114:117], v[154:157], v[186:189], v[114:117]
	v_mfma_f32_16x16x32_bf16 v[110:113], v[146:149], v[194:197], v[110:113]
	v_mfma_f32_16x16x32_bf16 v[106:109], v[154:157], v[194:197], v[106:109]
	v_mfma_f32_16x16x32_bf16 v[102:105], v[146:149], v[214:217], v[102:105]
	v_mfma_f32_16x16x32_bf16 v[98:101], v[154:157], v[214:217], v[98:101]
	v_mfma_f32_16x16x32_bf16 v[94:97], v[158:161], v[174:177], v[94:97]
	v_mfma_f32_16x16x32_bf16 v[90:93], v[166:169], v[174:177], v[90:93]
	v_mfma_f32_16x16x32_bf16 v[86:89], v[158:161], v[182:185], v[86:89]
	v_mfma_f32_16x16x32_bf16 v[82:85], v[166:169], v[182:185], v[82:85]
	v_mfma_f32_16x16x32_bf16 v[78:81], v[158:161], v[190:193], v[78:81]
	v_mfma_f32_16x16x32_bf16 v[74:77], v[166:169], v[190:193], v[74:77]
	v_mfma_f32_16x16x32_bf16 v[70:73], v[158:161], v[198:201], v[70:73]
	v_mfma_f32_16x16x32_bf16 v[66:69], v[166:169], v[198:201], v[66:69]
	v_mfma_f32_16x16x32_bf16 v[94:97], v[162:165], v[178:181], v[94:97]
	v_mfma_f32_16x16x32_bf16 v[90:93], v[170:173], v[178:181], v[90:93]
	v_mfma_f32_16x16x32_bf16 v[86:89], v[162:165], v[186:189], v[86:89]
	v_mfma_f32_16x16x32_bf16 v[82:85], v[170:173], v[186:189], v[82:85]
	v_mfma_f32_16x16x32_bf16 v[78:81], v[162:165], v[194:197], v[78:81]
	v_mfma_f32_16x16x32_bf16 v[74:77], v[170:173], v[194:197], v[74:77]
	v_mfma_f32_16x16x32_bf16 v[70:73], v[162:165], v[214:217], v[70:73]
	v_mfma_f32_16x16x32_bf16 v[66:69], v[170:173], v[214:217], v[66:69]
	s_barrier
	s_mov_b32 m0, s93
	v_lshl_add_u64 v[138:139], s[44:45], 0, v[202:203]
	ds_read_b128 v[174:177], v140 offset:16384
	ds_read_b128 v[178:181], v140 offset:17408
	ds_read_b128 v[182:185], v140 offset:18432
	ds_read_b128 v[186:189], v140 offset:19456
	ds_read_b128 v[190:193], v140 offset:20480
	ds_read_b128 v[194:197], v140 offset:21504
	ds_read_b128 v[198:201], v140 offset:22528
	ds_read_b128 v[214:217], v140 offset:23552
	global_load_lds_dwordx4 v[138:139], off
	v_lshl_add_u64 v[218:219], s[44:45], 0, v[134:135]
	s_mov_b32 m0, s85
	v_lshl_add_u64 v[220:221], s[46:47], 0, v[202:203]
	global_load_lds_dwordx4 v[218:219], off
	s_mov_b32 m0, s92
	v_lshl_add_u64 v[222:223], s[42:43], 0, v[132:133]
	global_load_lds_dwordx4 v[220:221], off
	v_lshl_add_u64 v[220:221], s[46:47], 0, v[134:135]
	s_mov_b32 m0, s91
	s_nop 0
	global_load_lds_dwordx4 v[220:221], off
	v_lshl_add_u64 v[220:221], s[42:43], 0, v[130:131]
	s_mov_b32 m0, s55
	s_nop 0
	global_load_lds_dwordx4 v[220:221], off
	s_mov_b32 m0, s60
	s_nop 0
	global_load_lds_dwordx4 v[222:223], off
	s_cmp_lg_u32 s100, 0
	s_cbranch_scc1 .Lch_rw2
	s_waitcnt vmcnt(8)
; #define PG8_STAGE(bufoff, gbase, voff) do { _Pragma("unroll") for (int _i = 0; _i < 2; ++_i) \
;         __builtin_amdgcn_global_load_lds((const GAS unsigned*)((const GAS char*)(gbase) + (voff)[_i]), (LAS unsigned*)(lds + (bufoff) + ldsw + _i * 8192), 16, 0, 0); } while (0)
; #define PG8_LDA(dst, b, h) do { _Pragma("unroll") for (int m = 0; m < 4; ++m) _Pragma("unroll") for (int k = 0; k < 2; ++k) dst[m][k] = *(const LAS bf16x8*)(lds + PG8_SA(b, h) + aoff + m * 2048 + k * 1024); } while (0)
; #define PG8_LDB(dst, b, h) do { _Pragma("unroll") for (int n = 0; n < 2; ++n) _Pragma("unroll") for (int k = 0; k < 2; ++k) dst[n][k] = *(const LAS bf16x8*)(lds + PG8_SB(b, h) + boff + n * 2048 + k * 1024); } while (0)
; #define PG8_MMA(ai, bj, At, Bt) do { __builtin_amdgcn_sched_barrier(0); _Pragma("unroll") for (int m = 0; m < 4; ++m) _Pragma("unroll") for (int n = 0; n < 2; ++n) _Pragma("unroll") for (int k = 0; k < 2; ++k) \
;         acc[ai][bj][m][n] = __builtin_amdgcn_mfma_f32_16x16x32_bf16(Bt[n][k], At[m][k], acc[ai][bj][m][n], 0, 0, 0); __builtin_amdgcn_sched_barrier(0); } while (0)
; #define PG8_WAIT_V(n) asm volatile("s_waitcnt vmcnt(" #n ")" ::: "memory")
; #define PG8_WAIT_L(n) asm volatile("s_waitcnt lgkmcnt(" #n ")" ::: "memory")
; #define PG8_BAR __builtin_amdgcn_s_barrier()
; #define PG8_SCHED __builtin_amdgcn_sched_barrier(0)
; template <class Epi, class Sched, bool ALIGN_EPI, bool SP2>
; __device__ __forceinline__ void gemm_phase(LAS unsigned char* lds, const int tid, const Gemm g, const Sched& S, const Epi& E) {
;     ...
;             PG8_WAIT_V(8); PG8_WAIT_L(0); PG8_BAR; PG8_MMA(1, 0, At, B0); PG8_MMA(1, 1, At, B1); PG8_BAR; PG8_SCHED;
;             PG8_LDB(B0, 1, 0); PG8_LDB(B1, 1, 1); PG8_SCHED; PG8_LDA(At, 1, 0); PG8_STAGE(PG8_SA(0, 1), a2 + hstepA, voffA);
;             PG8_WAIT_V(8); PG8_WAIT_L(0); PG8_BAR; PG8_MMA(0, 0, At, B0); PG8_MMA(0, 1, At, B1); PG8_BAR; PG8_SCHED;
.Lch_rj2:
	s_mov_b32 s100, 0
	s_waitcnt lgkmcnt(0)
	s_barrier
	s_waitcnt lgkmcnt(0)
	v_mfma_f32_16x16x32_bf16 v[62:65], v[142:145], v[174:177], v[62:65]
	v_mfma_f32_16x16x32_bf16 v[58:61], v[150:153], v[174:177], v[58:61]
	v_mfma_f32_16x16x32_bf16 v[54:57], v[142:145], v[182:185], v[54:57]
	v_mfma_f32_16x16x32_bf16 v[50:53], v[150:153], v[182:185], v[50:53]
	v_mfma_f32_16x16x32_bf16 v[46:49], v[142:145], v[190:193], v[46:49]
	v_mfma_f32_16x16x32_bf16 v[42:45], v[150:153], v[190:193], v[42:45]
	v_mfma_f32_16x16x32_bf16 v[38:41], v[142:145], v[198:201], v[38:41]
	v_mfma_f32_16x16x32_bf16 v[34:37], v[150:153], v[198:201], v[34:37]
	v_mfma_f32_16x16x32_bf16 v[62:65], v[146:149], v[178:181], v[62:65]
	v_mfma_f32_16x16x32_bf16 v[58:61], v[154:157], v[178:181], v[58:61]
	v_mfma_f32_16x16x32_bf16 v[54:57], v[146:149], v[186:189], v[54:57]
	v_mfma_f32_16x16x32_bf16 v[50:53], v[154:157], v[186:189], v[50:53]
	v_mfma_f32_16x16x32_bf16 v[46:49], v[146:149], v[194:197], v[46:49]
	v_mfma_f32_16x16x32_bf16 v[42:45], v[154:157], v[194:197], v[42:45]
	v_mfma_f32_16x16x32_bf16 v[38:41], v[146:149], v[214:217], v[38:41]
	v_mfma_f32_16x16x32_bf16 v[34:37], v[154:157], v[214:217], v[34:37]
	v_mfma_f32_16x16x32_bf16 v[30:33], v[158:161], v[174:177], v[30:33]
	v_mfma_f32_16x16x32_bf16 v[26:29], v[166:169], v[174:177], v[26:29]
	v_mfma_f32_16x16x32_bf16 v[22:25], v[158:161], v[182:185], v[22:25]
	v_mfma_f32_16x16x32_bf16 v[18:21], v[166:169], v[182:185], v[18:21]
	v_mfma_f32_16x16x32_bf16 v[14:17], v[158:161], v[190:193], v[14:17]
	v_mfma_f32_16x16x32_bf16 v[10:13], v[166:169], v[190:193], v[10:13]
	v_mfma_f32_16x16x32_bf16 v[6:9], v[158:161], v[198:201], v[6:9]
	v_mfma_f32_16x16x32_bf16 v[2:5], v[166:169], v[198:201], v[2:5]
	v_mfma_f32_16x16x32_bf16 v[30:33], v[162:165], v[178:181], v[30:33]
	v_mfma_f32_16x16x32_bf16 v[26:29], v[170:173], v[178:181], v[26:29]
	v_mfma_f32_16x16x32_bf16 v[22:25], v[162:165], v[186:189], v[22:25]
	v_mfma_f32_16x16x32_bf16 v[18:21], v[170:173], v[186:189], v[18:21]
	v_mfma_f32_16x16x32_bf16 v[14:17], v[162:165], v[194:197], v[14:17]
	v_mfma_f32_16x16x32_bf16 v[10:13], v[170:173], v[194:197], v[10:13]
	v_mfma_f32_16x16x32_bf16 v[6:9], v[162:165], v[214:217], v[6:9]
	v_mfma_f32_16x16x32_bf16 v[2:5], v[170:173], v[214:217], v[2:5]
	s_barrier
	v_add_u32_e32 v136, s82, v1
	ds_read_b128 v[142:145], v136
	ds_read_b128 v[146:149], v136 offset:1024
	ds_read_b128 v[150:153], v136 offset:2048
	ds_read_b128 v[154:157], v136 offset:3072
	v_add_u32_e32 v136, s73, v1
	ds_read_b128 v[158:161], v136
	ds_read_b128 v[162:165], v136 offset:1024
	ds_read_b128 v[166:169], v136 offset:2048
	ds_read_b128 v[170:173], v136 offset:3072
	s_mov_b32 m0, s61
	v_lshl_add_u64 v[224:225], s[34:35], 0, v[130:131]
	ds_read_b128 v[174:177], v140 offset:32768
	ds_read_b128 v[178:181], v140 offset:33792
	ds_read_b128 v[182:185], v140 offset:34816
	ds_read_b128 v[186:189], v140 offset:35840
	ds_read_b128 v[190:193], v140 offset:36864
	ds_read_b128 v[194:197], v140 offset:37888
	ds_read_b128 v[198:201], v140 offset:38912
	ds_read_b128 v[214:217], v140 offset:39936
	global_load_lds_dwordx4 v[224:225], off
	v_lshl_add_u64 v[224:225], s[34:35], 0, v[132:133]
	s_mov_b32 m0, s62
	s_nop 0
	global_load_lds_dwordx4 v[224:225], off
	s_waitcnt vmcnt(8)
	s_waitcnt lgkmcnt(0)
	s_barrier
	s_waitcnt lgkmcnt(0)
	v_mfma_f32_16x16x32_bf16 v[126:129], v[142:145], v[174:177], v[126:129]
	v_mfma_f32_16x16x32_bf16 v[122:125], v[150:153], v[174:177], v[122:125]
	v_mfma_f32_16x16x32_bf16 v[118:121], v[142:145], v[182:185], v[118:121]
	v_mfma_f32_16x16x32_bf16 v[114:117], v[150:153], v[182:185], v[114:117]
	v_mfma_f32_16x16x32_bf16 v[110:113], v[142:145], v[190:193], v[110:113]
	v_mfma_f32_16x16x32_bf16 v[106:109], v[150:153], v[190:193], v[106:109]
	v_mfma_f32_16x16x32_bf16 v[102:105], v[142:145], v[198:201], v[102:105]
	v_mfma_f32_16x16x32_bf16 v[98:101], v[150:153], v[198:201], v[98:101]
	v_mfma_f32_16x16x32_bf16 v[126:129], v[146:149], v[178:181], v[126:129]
	v_mfma_f32_16x16x32_bf16 v[122:125], v[154:157], v[178:181], v[122:125]
	v_mfma_f32_16x16x32_bf16 v[118:121], v[146:149], v[186:189], v[118:121]
	v_mfma_f32_16x16x32_bf16 v[114:117], v[154:157], v[186:189], v[114:117]
	v_mfma_f32_16x16x32_bf16 v[110:113], v[146:149], v[194:197], v[110:113]
	v_mfma_f32_16x16x32_bf16 v[106:109], v[154:157], v[194:197], v[106:109]
	v_mfma_f32_16x16x32_bf16 v[102:105], v[146:149], v[214:217], v[102:105]
	v_mfma_f32_16x16x32_bf16 v[98:101], v[154:157], v[214:217], v[98:101]
	v_mfma_f32_16x16x32_bf16 v[94:97], v[158:161], v[174:177], v[94:97]
	v_mfma_f32_16x16x32_bf16 v[90:93], v[166:169], v[174:177], v[90:93]
	v_mfma_f32_16x16x32_bf16 v[86:89], v[158:161], v[182:185], v[86:89]
	v_mfma_f32_16x16x32_bf16 v[82:85], v[166:169], v[182:185], v[82:85]
	v_mfma_f32_16x16x32_bf16 v[78:81], v[158:161], v[190:193], v[78:81]
	v_mfma_f32_16x16x32_bf16 v[74:77], v[166:169], v[190:193], v[74:77]
	v_mfma_f32_16x16x32_bf16 v[70:73], v[158:161], v[198:201], v[70:73]
	v_mfma_f32_16x16x32_bf16 v[66:69], v[166:169], v[198:201], v[66:69]
	v_mfma_f32_16x16x32_bf16 v[94:97], v[162:165], v[178:181], v[94:97]
	v_mfma_f32_16x16x32_bf16 v[90:93], v[170:173], v[178:181], v[90:93]
	v_mfma_f32_16x16x32_bf16 v[86:89], v[162:165], v[186:189], v[86:89]
	v_mfma_f32_16x16x32_bf16 v[82:85], v[170:173], v[186:189], v[82:85]
	v_mfma_f32_16x16x32_bf16 v[78:81], v[162:165], v[194:197], v[78:81]
	v_mfma_f32_16x16x32_bf16 v[74:77], v[170:173], v[194:197], v[74:77]
	v_mfma_f32_16x16x32_bf16 v[70:73], v[162:165], v[214:217], v[70:73]
	v_mfma_f32_16x16x32_bf16 v[66:69], v[170:173], v[214:217], v[66:69]
	s_barrier
; #define PG8_STAGE(bufoff, gbase, voff) do { _Pragma("unroll") for (int _i = 0; _i < 2; ++_i) \
;         __builtin_amdgcn_global_load_lds((const GAS unsigned*)((const GAS char*)(gbase) + (voff)[_i]), (LAS unsigned*)(lds + (bufoff) + ldsw + _i * 8192), 16, 0, 0); } while (0)
; #define PG8_LDA(dst, b, h) do { _Pragma("unroll") for (int m = 0; m < 4; ++m) _Pragma("unroll") for (int k = 0; k < 2; ++k) dst[m][k] = *(const LAS bf16x8*)(lds + PG8_SA(b, h) + aoff + m * 2048 + k * 1024); } while (0)
; #define PG8_WAIT_V(n) asm volatile("s_waitcnt vmcnt(" #n ")" ::: "memory")
; template <class Epi, class Sched, bool ALIGN_EPI, bool SP2>
; __device__ __forceinline__ void gemm_phase(LAS unsigned char* lds, const int tid, const Gemm g, const Sched& S, const Epi& E) {
;     ...
;             PG8_LDA(At, 1, 1); PG8_STAGE(PG8_SB(1, 0), b3, voffB); PG8_STAGE(PG8_SB(1, 1), b3 + hstepB, voffB); PG8_STAGE(PG8_SA(1, 0), a3, voffA);
;             PG8_WAIT_V(8); PG8_WAIT_L(0); PG8_BAR; PG8_MMA(1, 0, At, B0); PG8_MMA(1, 1, At, B1); PG8_BAR; PG8_SCHED;
;             } else {
;             PG8_LDB(B0, 0, 0); PG8_SCHED; PG8_LDA(At, 0, 0); PG8_STAGE(PG8_SA(1, 1), a1 + hstepA, voffA);
;             PG8_WAIT_L(8); PG8_BAR; PG8_WAIT_L(0); PG8_MMA(0, 0, At, B0); PG8_BAR; PG8_SCHED;
;             PG8_LDB(B1, 0, 1); PG8_STAGE(PG8_SB(0, 0), b2, voffB);
;             PG8_BAR; PG8_WAIT_L(0); PG8_MMA(0, 1, At, B1); PG8_BAR;
;             PG8_LDA(At, 0, 1); PG8_STAGE(PG8_SA(0, 0), a2, voffA);
;             PG8_BAR; PG8_WAIT_L(0); PG8_MMA(1, 0, At, B0); PG8_BAR; PG8_SCHED;
;             PG8_STAGE(PG8_SB(0, 1), b2 + hstepB, voffB);
;             PG8_WAIT_V(6); PG8_BAR; PG8_MMA(1, 1, At, B1); PG8_BAR;
;             PG8_LDB(B0, 1, 0); PG8_SCHED; PG8_LDA(At, 1, 0); PG8_STAGE(PG8_SA(0, 1), a2 + hstepA, voffA);
;             PG8_WAIT_L(8); PG8_BAR; PG8_WAIT_L(0); PG8_MMA(0, 0, At, B0); PG8_BAR; PG8_SCHED;
;             PG8_LDB(B1, 1, 1); PG8_STAGE(PG8_SB(1, 0), b3, voffB);
;             PG8_BAR; PG8_WAIT_L(0); PG8_MMA(0, 1, At, B1); PG8_BAR;
;             PG8_LDA(At, 1, 1); PG8_STAGE(PG8_SA(1, 0), a3, voffA);
;             PG8_BAR; PG8_WAIT_L(0); PG8_MMA(1, 0, At, B0); PG8_BAR; PG8_SCHED;
;             PG8_STAGE(PG8_SB(1, 1), b3 + hstepB, voffB);
;             PG8_WAIT_V(6); PG8_BAR; PG8_MMA(1, 1, At, B1); PG8_BAR;
;             }
;         }
;         if constexpr (ALIGN_EPI) { if (wr == 0) PG8_BAR; }
	s_mov_b32 m0, s72
	v_lshl_add_u64 v[138:139], v[138:139], 0, s[14:15]
	ds_read_b128 v[174:177], v140 offset:49152
	ds_read_b128 v[178:181], v140 offset:50176
	ds_read_b128 v[182:185], v140 offset:51200
	ds_read_b128 v[186:189], v140 offset:52224
	ds_read_b128 v[190:193], v140 offset:53248
	ds_read_b128 v[194:197], v140 offset:54272
	ds_read_b128 v[198:201], v140 offset:55296
	ds_read_b128 v[214:217], v140 offset:56320
	global_load_lds_dwordx4 v[138:139], off
	v_lshl_add_u64 v[138:139], v[218:219], 0, s[14:15]
	s_mov_b32 m0, s59
	s_nop 0
	global_load_lds_dwordx4 v[138:139], off
	v_lshl_add_u64 v[138:139], s[26:27], 0, v[202:203]
	s_mov_b32 m0, s95
	s_nop 0
	global_load_lds_dwordx4 v[138:139], off
	v_lshl_add_u64 v[138:139], s[26:27], 0, v[134:135]
	s_mov_b32 m0, s94
	s_nop 0
	global_load_lds_dwordx4 v[138:139], off
	v_lshl_add_u64 v[138:139], v[220:221], 0, s[14:15]
	s_mov_b32 m0, s63
	s_nop 0
	global_load_lds_dwordx4 v[138:139], off
	v_lshl_add_u64 v[138:139], v[222:223], 0, s[14:15]
	s_mov_b32 m0, s64
	s_nop 0
	global_load_lds_dwordx4 v[138:139], off
	s_waitcnt vmcnt(8)
	s_waitcnt lgkmcnt(0)
	s_barrier
	s_waitcnt lgkmcnt(0)
	v_mfma_f32_16x16x32_bf16 v[62:65], v[142:145], v[174:177], v[62:65]
	v_mfma_f32_16x16x32_bf16 v[58:61], v[150:153], v[174:177], v[58:61]
	v_mfma_f32_16x16x32_bf16 v[54:57], v[142:145], v[182:185], v[54:57]
	v_mfma_f32_16x16x32_bf16 v[50:53], v[150:153], v[182:185], v[50:53]
	v_mfma_f32_16x16x32_bf16 v[46:49], v[142:145], v[190:193], v[46:49]
	v_mfma_f32_16x16x32_bf16 v[42:45], v[150:153], v[190:193], v[42:45]
	v_mfma_f32_16x16x32_bf16 v[38:41], v[142:145], v[198:201], v[38:41]
	v_mfma_f32_16x16x32_bf16 v[34:37], v[150:153], v[198:201], v[34:37]
	v_mfma_f32_16x16x32_bf16 v[62:65], v[146:149], v[178:181], v[62:65]
	v_mfma_f32_16x16x32_bf16 v[58:61], v[154:157], v[178:181], v[58:61]
	v_mfma_f32_16x16x32_bf16 v[54:57], v[146:149], v[186:189], v[54:57]
	v_mfma_f32_16x16x32_bf16 v[50:53], v[154:157], v[186:189], v[50:53]
	v_mfma_f32_16x16x32_bf16 v[46:49], v[146:149], v[194:197], v[46:49]
	v_mfma_f32_16x16x32_bf16 v[42:45], v[154:157], v[194:197], v[42:45]
	v_mfma_f32_16x16x32_bf16 v[38:41], v[146:149], v[214:217], v[38:41]
	v_mfma_f32_16x16x32_bf16 v[34:37], v[154:157], v[214:217], v[34:37]
	v_mfma_f32_16x16x32_bf16 v[30:33], v[158:161], v[174:177], v[30:33]
	v_mfma_f32_16x16x32_bf16 v[26:29], v[166:169], v[174:177], v[26:29]
	v_mfma_f32_16x16x32_bf16 v[22:25], v[158:161], v[182:185], v[22:25]
	v_mfma_f32_16x16x32_bf16 v[18:21], v[166:169], v[182:185], v[18:21]
	v_mfma_f32_16x16x32_bf16 v[14:17], v[158:161], v[190:193], v[14:17]
	v_mfma_f32_16x16x32_bf16 v[10:13], v[166:169], v[190:193], v[10:13]
	v_mfma_f32_16x16x32_bf16 v[6:9], v[158:161], v[198:201], v[6:9]
	v_mfma_f32_16x16x32_bf16 v[2:5], v[166:169], v[198:201], v[2:5]
	v_mfma_f32_16x16x32_bf16 v[30:33], v[162:165], v[178:181], v[30:33]
	v_mfma_f32_16x16x32_bf16 v[26:29], v[170:173], v[178:181], v[26:29]
	v_mfma_f32_16x16x32_bf16 v[22:25], v[162:165], v[186:189], v[22:25]
	v_mfma_f32_16x16x32_bf16 v[18:21], v[170:173], v[186:189], v[18:21]
	v_mfma_f32_16x16x32_bf16 v[14:17], v[162:165], v[194:197], v[14:17]
	v_mfma_f32_16x16x32_bf16 v[10:13], v[170:173], v[194:197], v[10:13]
	v_mfma_f32_16x16x32_bf16 v[6:9], v[162:165], v[214:217], v[6:9]
	v_mfma_f32_16x16x32_bf16 v[2:5], v[170:173], v[214:217], v[2:5]
	s_barrier
	s_andn2_b64 vcc, exec, s[24:25]
	s_mov_b64 s[26:27], -1
	s_mov_b64 s[24:25], 0
	s_mov_b64 s[34:35], 0x100
	s_cbranch_vccz .LBB0_748
	s_and_b64 vcc, exec, s[6:7]
	s_cbranch_vccz .LBB0_751
	s_barrier

; #define GAS __attribute__((address_space(1)))
; __device__ __forceinline__ unsigned cvt_pk_bf16(float lo, float hi) { unsigned r; asm volatile("v_cvt_pk_bf16_f32 %0, %1, %2" : "=v"(r) : "v"(lo), "v"(hi)); return r; }
;     __device__ __forceinline__ void operator()(const f32x4 (&acc)[2][2][4][2], const Unit& u, int wr, int wc, int fr, int fq) const { base(acc, u, wr, wc, fr, fq); }
;     __device__ __forceinline__ void operator()(f32x4 (&acc)[2][2][4][2], const Unit& u, int wr, int wc, int fr, int fq) const {
;         const int s = u.pm, dir = u.pn, bh = u.z / 9, h = bh & 3;
;         const float cdec = cd[dir * 4 + h];
;         const int cn = dir == 0 ? s + 1 : 8 - s;
;         int eoff = (wr * 64 + fr) * 768 + 256 + dir * 256 + wc * 32 + 8 * fq; asm volatile("" : "+v"(eoff));
;         GAS bf16_t* dst = BB + (size_t)(bh * 9 + cn) * 256 * 768 + eoff;
;         if (s == 0) {
;             GAS bf16_t* d0 = BB + (size_t)(bh * 9) * 256 * 768 + eoff;
; #pragma unroll
;             for (int ai = 0; ai < 2; ++ai)
; #pragma unroll
;                 for (int m = 0; m < 4; ++m)
; #pragma unroll
;                     for (int bj = 0; bj < 2; ++bj) *(GAS u32x4*)(d0 + (size_t)(ai * HALF + m * 16) * 768 + bj * HALF) = (u32x4){0u, 0u, 0u, 0u};
;         }
; #pragma unroll
;         for (int ai = 0; ai < 2; ++ai)
; #pragma unroll
;             for (int m = 0; m < 4; ++m) {
; #pragma unroll
;                 for (int bj = 0; bj < 2; ++bj) { const f32x4 v0 = acc[ai][bj][m][0], v1 = acc[ai][bj][m][1];
;                     u32x4 w; w.x = cvt_pk_bf16(v0[0], v0[1]); w.y = cvt_pk_bf16(v0[2], v0[3]); w.z = cvt_pk_bf16(v1[0], v1[1]); w.w = cvt_pk_bf16(v1[2], v1[3]);
;                     *(GAS u32x4*)(dst + (size_t)(ai * HALF + m * 16) * 768 + bj * HALF) = w;
;                     acc[ai][bj][m][0] = v0 * cdec; acc[ai][bj][m][1] = v1 * cdec; }
;                 asm volatile("" ::: "memory"); }
;     }
.LBB0_753:
	s_add_i32 s18, s70, 1
	s_sub_i32 s19, 8, s70
	s_cmp_eq_u32 s71, 0
	s_cselect_b32 s18, s18, s19
	s_add_i32 s9, s18, s9
	s_mul_hi_i32 s19, s9, 0x60000
	s_mul_i32 s9, s9, 0x60000
	s_add_u32 s18, s5, s9
	s_addc_u32 s19, s52, s19
	v_lshl_add_u64 v[138:139], v[138:139], 1, s[18:19]
	v_cvt_pk_bf16_f32 v142, v126, v127
	v_cvt_pk_bf16_f32 v143, v128, v129
	v_cvt_pk_bf16_f32 v144, v122, v123
	v_cvt_pk_bf16_f32 v145, v124, v125
	global_store_dwordx4 v[138:139], v[142:145], off
	v_add_co_u32_e32 v146, vcc, s74, v138
	s_nop 0
	v_cvt_pk_bf16_f32 v142, v94, v95
	v_cvt_pk_bf16_f32 v143, v96, v97
	v_cvt_pk_bf16_f32 v144, v90, v91
	v_cvt_pk_bf16_f32 v145, v92, v93
	global_store_dwordx4 v[138:139], v[142:145], off offset:256
	v_addc_co_u32_e32 v147, vcc, 0, v139, vcc
	s_nop 0
	v_cvt_pk_bf16_f32 v142, v118, v119
	v_cvt_pk_bf16_f32 v143, v120, v121
	v_cvt_pk_bf16_f32 v144, v114, v115
	v_cvt_pk_bf16_f32 v145, v116, v117
	s_mov_b32 s9, 0xc000
	global_store_dwordx4 v[146:147], v[142:145], off
	s_mov_b64 s[18:19], -1
	s_nop 0
	v_cvt_pk_bf16_f32 v142, v86, v87
	v_cvt_pk_bf16_f32 v143, v88, v89
	v_cvt_pk_bf16_f32 v144, v82, v83
	v_cvt_pk_bf16_f32 v145, v84, v85
	global_store_dwordx4 v[146:147], v[142:145], off offset:256
	v_add_co_u32_e32 v146, vcc, s9, v138
	s_nop 0
	v_cvt_pk_bf16_f32 v142, v110, v111
	v_cvt_pk_bf16_f32 v143, v112, v113
	v_cvt_pk_bf16_f32 v144, v106, v107
	v_cvt_pk_bf16_f32 v145, v108, v109
	s_nop 0
	v_addc_co_u32_e32 v147, vcc, 0, v139, vcc
	s_mov_b32 s9, 0x12000
	global_store_dwordx4 v[146:147], v[142:145], off
	s_nop 1
	v_cvt_pk_bf16_f32 v142, v78, v79
	v_cvt_pk_bf16_f32 v143, v80, v81
	v_cvt_pk_bf16_f32 v144, v74, v75
	v_cvt_pk_bf16_f32 v145, v76, v77
	global_store_dwordx4 v[146:147], v[142:145], off offset:256
	v_add_co_u32_e32 v146, vcc, s9, v138
	s_nop 0
	v_cvt_pk_bf16_f32 v142, v102, v103
	v_cvt_pk_bf16_f32 v143, v104, v105
	v_cvt_pk_bf16_f32 v144, v98, v99
	v_cvt_pk_bf16_f32 v145, v100, v101
	s_nop 0
	v_addc_co_u32_e32 v147, vcc, 0, v139, vcc
	s_mov_b32 s9, 0x30000
	global_store_dwordx4 v[146:147], v[142:145], off
	s_nop 1
	v_cvt_pk_bf16_f32 v142, v70, v71
	v_cvt_pk_bf16_f32 v143, v72, v73
	v_cvt_pk_bf16_f32 v144, v66, v67
	v_cvt_pk_bf16_f32 v145, v68, v69
	global_store_dwordx4 v[146:147], v[142:145], off offset:256
	v_add_co_u32_e32 v146, vcc, s9, v138
	s_nop 0
	v_cvt_pk_bf16_f32 v142, v62, v63
	v_cvt_pk_bf16_f32 v143, v64, v65
	v_cvt_pk_bf16_f32 v144, v58, v59
	v_cvt_pk_bf16_f32 v145, v60, v61
	s_nop 0
	v_addc_co_u32_e32 v147, vcc, 0, v139, vcc
	s_mov_b32 s9, 0x36000
	global_store_dwordx4 v[146:147], v[142:145], off
	s_nop 1
	v_cvt_pk_bf16_f32 v142, v30, v31
	v_cvt_pk_bf16_f32 v143, v32, v33
	v_cvt_pk_bf16_f32 v144, v26, v27
	v_cvt_pk_bf16_f32 v145, v28, v29
	global_store_dwordx4 v[146:147], v[142:145], off offset:256
	v_add_co_u32_e32 v146, vcc, s9, v138
	s_nop 0
	v_cvt_pk_bf16_f32 v142, v54, v55
	v_cvt_pk_bf16_f32 v143, v56, v57
	v_cvt_pk_bf16_f32 v144, v50, v51
	v_cvt_pk_bf16_f32 v145, v52, v53
	s_nop 0
	v_addc_co_u32_e32 v147, vcc, 0, v139, vcc
	s_mov_b32 s9, 0x3c000
	global_store_dwordx4 v[146:147], v[142:145], off
	s_nop 1
	v_cvt_pk_bf16_f32 v142, v22, v23
	v_cvt_pk_bf16_f32 v143, v24, v25
	v_cvt_pk_bf16_f32 v144, v18, v19
	v_cvt_pk_bf16_f32 v145, v20, v21
	global_store_dwordx4 v[146:147], v[142:145], off offset:256
	v_add_co_u32_e32 v146, vcc, s9, v138
	s_nop 0
	v_cvt_pk_bf16_f32 v142, v46, v47
	v_cvt_pk_bf16_f32 v143, v48, v49
	v_cvt_pk_bf16_f32 v144, v42, v43
	v_cvt_pk_bf16_f32 v145, v44, v45
	s_nop 0
	v_addc_co_u32_e32 v147, vcc, 0, v139, vcc
	s_mov_b32 s9, 0x42000
	global_store_dwordx4 v[146:147], v[142:145], off
	v_add_co_u32_e32 v138, vcc, s9, v138
	s_nop 0
	v_cvt_pk_bf16_f32 v142, v14, v15
	v_cvt_pk_bf16_f32 v143, v16, v17
	v_cvt_pk_bf16_f32 v144, v10, v11
	v_cvt_pk_bf16_f32 v145, v12, v13
	global_store_dwordx4 v[146:147], v[142:145], off offset:256
	v_addc_co_u32_e32 v139, vcc, 0, v139, vcc
	s_nop 0
	v_cvt_pk_bf16_f32 v142, v38, v39
	v_cvt_pk_bf16_f32 v143, v40, v41
	v_cvt_pk_bf16_f32 v144, v34, v35
	v_cvt_pk_bf16_f32 v145, v36, v37
	global_store_dwordx4 v[138:139], v[142:145], off
	s_and_b64 vcc, exec, s[40:41]
	s_nop 0
	v_cvt_pk_bf16_f32 v142, v6, v7
	v_cvt_pk_bf16_f32 v143, v8, v9
	v_cvt_pk_bf16_f32 v144, v2, v3
	v_cvt_pk_bf16_f32 v145, v4, v5
	global_store_dwordx4 v[138:139], v[142:145], off offset:256
	s_cbranch_vccnz .LBB0_742
	s_cmp_lg_u32 s70, 7
	s_cbranch_scc1 .LBB0_756
; template <class Epi, class Sched, bool ALIGN_EPI, bool SP2>
; __device__ __forceinline__ void gemm_phase(LAS unsigned char* lds, const int tid, const Gemm g, const Sched& S, const Epi& E) {
;     ...
;         if (!has_next) break;
;         bool rst = true; if constexpr (Epi::KEEPS) rst = E.reset(cur);
;         if (rst) {
; #pragma unroll
;         for (int a = 0; a < 2; ++a)
; #pragma unroll
;             for (int b = 0; b < 2; ++b)
; #pragma unroll
;                 for (int m = 0; m < 4; ++m)
; #pragma unroll
;                     for (int n = 0; n < 2; ++n) acc[a][b][m][n] = (f32x4){0.f, 0.f, 0.f, 0.f};
;         }
;         cur = nxt; cA = nA; cB = nB; ++ui;
	s_mov_b32 s100, 0
	v_mov_b32_e32 v2, 0
	v_mov_b32_e32 v3, v2
	v_mov_b32_e32 v4, v2
	v_mov_b32_e32 v5, v2
	v_mov_b32_e32 v6, v2
	v_mov_b32_e32 v7, v2
	v_mov_b32_e32 v8, v2
	v_mov_b32_e32 v9, v2
	v_mov_b32_e32 v10, v2
	v_mov_b32_e32 v11, v2
	v_mov_b32_e32 v12, v2
	v_mov_b32_e32 v13, v2
	v_mov_b32_e32 v14, v2
	v_mov_b32_e32 v15, v2
	v_mov_b32_e32 v16, v2
	v_mov_b32_e32 v17, v2
	v_mov_b32_e32 v18, v2
	v_mov_b32_e32 v19, v2
	v_mov_b32_e32 v20, v2
	v_mov_b32_e32 v21, v2
	v_mov_b32_e32 v22, v2
	v_mov_b32_e32 v23, v2
	v_mov_b32_e32 v24, v2
	v_mov_b32_e32 v25, v2
	v_mov_b32_e32 v26, v2
	v_mov_b32_e32 v27, v2
	v_mov_b32_e32 v28, v2
	v_mov_b32_e32 v29, v2
	v_mov_b32_e32 v30, v2
	v_mov_b32_e32 v31, v2
	v_mov_b32_e32 v32, v2
	v_mov_b32_e32 v33, v2
	v_mov_b32_e32 v34, v2
	v_mov_b32_e32 v35, v2
	v_mov_b32_e32 v36, v2
	v_mov_b32_e32 v37, v2
	v_mov_b32_e32 v38, v2
	v_mov_b32_e32 v39, v2
	v_mov_b32_e32 v40, v2
	v_mov_b32_e32 v41, v2
	v_mov_b32_e32 v42, v2
	v_mov_b32_e32 v43, v2
	v_mov_b32_e32 v44, v2
	v_mov_b32_e32 v45, v2
	v_mov_b32_e32 v46, v2
	v_mov_b32_e32 v47, v2
	v_mov_b32_e32 v48, v2
	v_mov_b32_e32 v49, v2
	v_mov_b32_e32 v50, v2
	v_mov_b32_e32 v51, v2
	v_mov_b32_e32 v52, v2
	v_mov_b32_e32 v53, v2
	v_mov_b32_e32 v54, v2
	v_mov_b32_e32 v55, v2
	v_mov_b32_e32 v56, v2
	v_mov_b32_e32 v57, v2
	v_mov_b32_e32 v58, v2
	v_mov_b32_e32 v59, v2
	v_mov_b32_e32 v60, v2
	v_mov_b32_e32 v61, v2
	v_mov_b32_e32 v62, v2
	v_mov_b32_e32 v63, v2
	v_mov_b32_e32 v64, v2
	v_mov_b32_e32 v65, v2
	v_mov_b32_e32 v66, v2
	v_mov_b32_e32 v67, v2
	v_mov_b32_e32 v68, v2
	v_mov_b32_e32 v69, v2
	v_mov_b32_e32 v70, v2
	v_mov_b32_e32 v71, v2
	v_mov_b32_e32 v72, v2
	v_mov_b32_e32 v73, v2
	v_mov_b32_e32 v74, v2
	v_mov_b32_e32 v75, v2
	v_mov_b32_e32 v76, v2
	v_mov_b32_e32 v77, v2
	v_mov_b32_e32 v78, v2
	v_mov_b32_e32 v79, v2
	v_mov_b32_e32 v80, v2
	v_mov_b32_e32 v81, v2
	v_mov_b32_e32 v82, v2
	v_mov_b32_e32 v83, v2
	v_mov_b32_e32 v84, v2
	v_mov_b32_e32 v85, v2
	v_mov_b32_e32 v86, v2
	v_mov_b32_e32 v87, v2
	v_mov_b32_e32 v88, v2
	v_mov_b32_e32 v89, v2
	v_mov_b32_e32 v90, v2
	v_mov_b32_e32 v91, v2
	v_mov_b32_e32 v92, v2
	v_mov_b32_e32 v93, v2
	v_mov_b32_e32 v94, v2
	v_mov_b32_e32 v95, v2
	v_mov_b32_e32 v96, v2
	v_mov_b32_e32 v97, v2
	v_mov_b32_e32 v98, v2
	v_mov_b32_e32 v99, v2
	v_mov_b32_e32 v100, v2
	v_mov_b32_e32 v101, v2
	v_mov_b32_e32 v102, v2
	v_mov_b32_e32 v103, v2
	v_mov_b32_e32 v104, v2
	v_mov_b32_e32 v105, v2
	v_mov_b32_e32 v106, v2
	v_mov_b32_e32 v107, v2
	v_mov_b32_e32 v108, v2
	v_mov_b32_e32 v109, v2
	v_mov_b32_e32 v110, v2
	v_mov_b32_e32 v111, v2
	v_mov_b32_e32 v112, v2
	v_mov_b32_e32 v113, v2
	v_mov_b32_e32 v114, v2
	v_mov_b32_e32 v115, v2
	v_mov_b32_e32 v116, v2
	v_mov_b32_e32 v117, v2
	v_mov_b32_e32 v118, v2
	v_mov_b32_e32 v119, v2
	v_mov_b32_e32 v120, v2
	v_mov_b32_e32 v121, v2
	v_mov_b32_e32 v122, v2
	v_mov_b32_e32 v123, v2
	v_mov_b32_e32 v124, v2
	v_mov_b32_e32 v125, v2
	v_mov_b32_e32 v126, v2
	v_mov_b32_e32 v127, v2
	v_mov_b32_e32 v128, v2
	v_mov_b32_e32 v129, v2
	s_and_b64 vcc, exec, s[38:39]
	s_cbranch_vccnz .LBB0_741
	s_branch .LBB0_740
; #define GAS __attribute__((address_space(1)))
; __device__ __forceinline__ unsigned cvt_pk_bf16(float lo, float hi) { unsigned r; asm volatile("v_cvt_pk_bf16_f32 %0, %1, %2" : "=v"(r) : "v"(lo), "v"(hi)); return r; }
; #define PG8_STAGE(bufoff, gbase, voff) do { _Pragma("unroll") for (int _i = 0; _i < 2; ++_i) \
;         __builtin_amdgcn_global_load_lds((const GAS unsigned*)((const GAS char*)(gbase) + (voff)[_i]), (LAS unsigned*)(lds + (bufoff) + ldsw + _i * 8192), 16, 0, 0); } while (0)
; #define PG8_LDA(dst, b, h) do { _Pragma("unroll") for (int m = 0; m < 4; ++m) _Pragma("unroll") for (int k = 0; k < 2; ++k) dst[m][k] = *(const LAS bf16x8*)(lds + PG8_SA(b, h) + aoff + m * 2048 + k * 1024); } while (0)
; #define PG8_LDB(dst, b, h) do { _Pragma("unroll") for (int n = 0; n < 2; ++n) _Pragma("unroll") for (int k = 0; k < 2; ++k) dst[n][k] = *(const LAS bf16x8*)(lds + PG8_SB(b, h) + boff + n * 2048 + k * 1024); } while (0)
; #define PG8_MMA(ai, bj, At, Bt) do { __builtin_amdgcn_sched_barrier(0); _Pragma("unroll") for (int m = 0; m < 4; ++m) _Pragma("unroll") for (int n = 0; n < 2; ++n) _Pragma("unroll") for (int k = 0; k < 2; ++k) \
;         acc[ai][bj][m][n] = __builtin_amdgcn_mfma_f32_16x16x32_bf16(Bt[n][k], At[m][k], acc[ai][bj][m][n], 0, 0, 0); __builtin_amdgcn_sched_barrier(0); } while (0)
; #define PG8_BAR __builtin_amdgcn_s_barrier()
; template <class Epi, class Sched, bool ALIGN_EPI, bool SP2>
; __device__ __forceinline__ void gemm_phase(LAS unsigned char* lds, const int tid, const Gemm g, const Sched& S, const Epi& E) {
;     ...
;             PG8_LDB(B0, 0, 0); PG8_LDB(B1, 0, 1); PG8_SCHED; PG8_LDA(At, 0, 0); PG8_STAGE(PG8_SA(1, 1), a1 + hstepA, voffA);
;             PG8_WAIT_V(8); PG8_WAIT_L(0); PG8_BAR; PG8_MMA(0, 0, At, B0); PG8_MMA(0, 1, At, B1); PG8_BAR; PG8_SCHED;
;     __device__ __forceinline__ void operator()(f32x4 (&acc)[2][2][4][2], const Unit& u, int wr, int wc, int fr, int fq) const {
;     ...
;                 for (int bj = 0; bj < 2; ++bj) { const f32x4 v0 = acc[ai][bj][m][0], v1 = acc[ai][bj][m][1];
;                     u32x4 w; w.x = cvt_pk_bf16(v0[0], v0[1]); w.y = cvt_pk_bf16(v0[2], v0[3]); w.z = cvt_pk_bf16(v1[0], v1[1]); w.w = cvt_pk_bf16(v1[2], v1[3]);
;                     *(GAS u32x4*)(dst + (size_t)(ai * HALF + m * 16) * 768 + bj * HALF) = w;
;                     acc[ai][bj][m][0] = v0 * cdec; acc[ai][bj][m][1] = v1 * cdec; }
.LBB0_756:
	s_cmp_lg_u32 s70, 0
	s_cselect_b32 s100, 1, 0
	s_waitcnt lgkmcnt(0)
	v_pk_mul_f32 v[4:5], v[4:5], v[136:137] op_sel_hi:[1,0]
	v_pk_mul_f32 v[2:3], v[2:3], v[136:137] op_sel_hi:[1,0]
	v_pk_mul_f32 v[8:9], v[8:9], v[136:137] op_sel_hi:[1,0]
	v_pk_mul_f32 v[6:7], v[6:7], v[136:137] op_sel_hi:[1,0]
	v_pk_mul_f32 v[36:37], v[36:37], v[136:137] op_sel_hi:[1,0]
	v_pk_mul_f32 v[34:35], v[34:35], v[136:137] op_sel_hi:[1,0]
	v_pk_mul_f32 v[40:41], v[40:41], v[136:137] op_sel_hi:[1,0]
	v_pk_mul_f32 v[38:39], v[38:39], v[136:137] op_sel_hi:[1,0]
	v_pk_mul_f32 v[12:13], v[12:13], v[136:137] op_sel_hi:[1,0]
	v_pk_mul_f32 v[10:11], v[10:11], v[136:137] op_sel_hi:[1,0]
	v_pk_mul_f32 v[16:17], v[16:17], v[136:137] op_sel_hi:[1,0]
	v_pk_mul_f32 v[14:15], v[14:15], v[136:137] op_sel_hi:[1,0]
	v_pk_mul_f32 v[44:45], v[44:45], v[136:137] op_sel_hi:[1,0]
	v_pk_mul_f32 v[42:43], v[42:43], v[136:137] op_sel_hi:[1,0]
	v_pk_mul_f32 v[48:49], v[48:49], v[136:137] op_sel_hi:[1,0]
	v_pk_mul_f32 v[46:47], v[46:47], v[136:137] op_sel_hi:[1,0]
	v_pk_mul_f32 v[20:21], v[20:21], v[136:137] op_sel_hi:[1,0]
	v_pk_mul_f32 v[18:19], v[18:19], v[136:137] op_sel_hi:[1,0]
	v_pk_mul_f32 v[24:25], v[24:25], v[136:137] op_sel_hi:[1,0]
	v_pk_mul_f32 v[22:23], v[22:23], v[136:137] op_sel_hi:[1,0]
	v_pk_mul_f32 v[52:53], v[52:53], v[136:137] op_sel_hi:[1,0]
	v_pk_mul_f32 v[50:51], v[50:51], v[136:137] op_sel_hi:[1,0]
	v_pk_mul_f32 v[56:57], v[56:57], v[136:137] op_sel_hi:[1,0]
	v_pk_mul_f32 v[54:55], v[54:55], v[136:137] op_sel_hi:[1,0]
	v_pk_mul_f32 v[28:29], v[28:29], v[136:137] op_sel_hi:[1,0]
	v_pk_mul_f32 v[26:27], v[26:27], v[136:137] op_sel_hi:[1,0]
	v_pk_mul_f32 v[32:33], v[32:33], v[136:137] op_sel_hi:[1,0]
	v_pk_mul_f32 v[30:31], v[30:31], v[136:137] op_sel_hi:[1,0]
	v_pk_mul_f32 v[60:61], v[60:61], v[136:137] op_sel_hi:[1,0]
	v_pk_mul_f32 v[58:59], v[58:59], v[136:137] op_sel_hi:[1,0]
	v_pk_mul_f32 v[64:65], v[64:65], v[136:137] op_sel_hi:[1,0]
	v_pk_mul_f32 v[62:63], v[62:63], v[136:137] op_sel_hi:[1,0]
	v_pk_mul_f32 v[68:69], v[68:69], v[136:137] op_sel_hi:[1,0]
	v_pk_mul_f32 v[66:67], v[66:67], v[136:137] op_sel_hi:[1,0]
	v_pk_mul_f32 v[72:73], v[72:73], v[136:137] op_sel_hi:[1,0]
	v_pk_mul_f32 v[70:71], v[70:71], v[136:137] op_sel_hi:[1,0]
	v_pk_mul_f32 v[100:101], v[100:101], v[136:137] op_sel_hi:[1,0]
	v_pk_mul_f32 v[98:99], v[98:99], v[136:137] op_sel_hi:[1,0]
	v_pk_mul_f32 v[104:105], v[104:105], v[136:137] op_sel_hi:[1,0]
	v_pk_mul_f32 v[102:103], v[102:103], v[136:137] op_sel_hi:[1,0]
	v_pk_mul_f32 v[76:77], v[76:77], v[136:137] op_sel_hi:[1,0]
	v_pk_mul_f32 v[74:75], v[74:75], v[136:137] op_sel_hi:[1,0]
	v_pk_mul_f32 v[80:81], v[80:81], v[136:137] op_sel_hi:[1,0]
	v_pk_mul_f32 v[78:79], v[78:79], v[136:137] op_sel_hi:[1,0]
	v_pk_mul_f32 v[108:109], v[108:109], v[136:137] op_sel_hi:[1,0]
	v_pk_mul_f32 v[106:107], v[106:107], v[136:137] op_sel_hi:[1,0]
	v_pk_mul_f32 v[112:113], v[112:113], v[136:137] op_sel_hi:[1,0]
	v_pk_mul_f32 v[110:111], v[110:111], v[136:137] op_sel_hi:[1,0]
	v_pk_mul_f32 v[84:85], v[84:85], v[136:137] op_sel_hi:[1,0]
	v_pk_mul_f32 v[82:83], v[82:83], v[136:137] op_sel_hi:[1,0]
	v_pk_mul_f32 v[88:89], v[88:89], v[136:137] op_sel_hi:[1,0]
	v_pk_mul_f32 v[86:87], v[86:87], v[136:137] op_sel_hi:[1,0]
	v_pk_mul_f32 v[116:117], v[116:117], v[136:137] op_sel_hi:[1,0]
	v_pk_mul_f32 v[114:115], v[114:115], v[136:137] op_sel_hi:[1,0]
	v_pk_mul_f32 v[120:121], v[120:121], v[136:137] op_sel_hi:[1,0]
	v_pk_mul_f32 v[118:119], v[118:119], v[136:137] op_sel_hi:[1,0]
	v_pk_mul_f32 v[92:93], v[92:93], v[136:137] op_sel_hi:[1,0]
	v_pk_mul_f32 v[90:91], v[90:91], v[136:137] op_sel_hi:[1,0]
	v_pk_mul_f32 v[96:97], v[96:97], v[136:137] op_sel_hi:[1,0]
	v_pk_mul_f32 v[94:95], v[94:95], v[136:137] op_sel_hi:[1,0]
	v_pk_mul_f32 v[124:125], v[124:125], v[136:137] op_sel_hi:[1,0]
	v_pk_mul_f32 v[122:123], v[122:123], v[136:137] op_sel_hi:[1,0]
	v_pk_mul_f32 v[128:129], v[128:129], v[136:137] op_sel_hi:[1,0]
	v_pk_mul_f32 v[126:127], v[126:127], v[136:137] op_sel_hi:[1,0]
	s_and_b64 vcc, exec, s[38:39]
	s_cbranch_vccnz .LBB0_741
	s_branch .LBB0_740
.Lch_rw1:
	s_waitcnt vmcnt(24)
	s_branch .Lch_rj1

; #define GAS __attribute__((address_space(1)))
; __device__ __forceinline__ unsigned cvt_pk_bf16(float lo, float hi) { unsigned r; asm volatile("v_cvt_pk_bf16_f32 %0, %1, %2" : "=v"(r) : "v"(lo), "v"(hi)); return r; }
; #define PG8_WAIT_V(n) asm volatile("s_waitcnt vmcnt(" #n ")" ::: "memory")
; #define PG8_BAR __builtin_amdgcn_s_barrier()
; template <class Epi, class Sched, bool ALIGN_EPI, bool SP2>
; __device__ __forceinline__ void gemm_phase(LAS unsigned char* lds, const int tid, const Gemm g, const Sched& S, const Epi& E) {
;     ...
;     const GAS char* cA = S.aptr(cur); const GAS char* cB = S.bptr(cur);
;     if constexpr (SP2) {
;         PG8_STAGE(PG8_SB(0, 0), cB, voffB); PG8_STAGE(PG8_SB(0, 1), cB + hstepB, voffB); PG8_STAGE(PG8_SA(0, 0), cA, voffA); PG8_STAGE(PG8_SA(0, 1), cA + hstepA, voffA);
;         if (wr == 1) PG8_BAR;
;         PG8_WAIT_V(2); PG8_BAR;
;         PG8_STAGE(PG8_SB(1, 0), cB + kstep, voffB); PG8_STAGE(PG8_SA(1, 0), cA + kstep, voffA); PG8_STAGE(PG8_SB(1, 1), cB + hstepB + kstep, voffB);
;         PG8_WAIT_V(6); PG8_BAR;
;     __device__ __forceinline__ void operator()(const f32x4 (&acc)[2][2][4][2], const Unit& u, int wr, int wc, int fr, int fq) const {
;         const int row0 = u.pm * BM + wr * 64 + fr, col0 = u.pn * BM + wc * 32 + 8 * fq;
;         f32x4 bv[2][2];
; #pragma unroll
;         for (int bj = 0; bj < 2; ++bj)
; #pragma unroll
;             for (int n = 0; n < 2; ++n) bv[bj][n] = bias ? *(const GAS f32x4*)(bias + col0 + bj * HALF + 4 * n) : (f32x4){0.f, 0.f, 0.f, 0.f};
; #pragma unroll
;         for (int ai = 0; ai < 2; ++ai)
; #pragma unroll
;             for (int m = 0; m < 4; ++m) { GAS bf16_t* rowp = O + (size_t)(row0 + ai * HALF + m * 16) * ldc + col0;
; #pragma unroll
;                 for (int bj = 0; bj < 2; ++bj) { f32x4 v0 = acc[ai][bj][m][0] + bv[bj][0], v1 = acc[ai][bj][m][1] + bv[bj][1];
;                     if (ACT == 1) {
; #pragma unroll
;                         for (int j = 0; j < 4; ++j) { const float a = fmaxf(v0[j], 0.f), b = fmaxf(v1[j], 0.f); v0[j] = a * a; v1[j] = b * b; } }
;                     u32x4 w; w.x = cvt_pk_bf16(v0[0], v0[1]); w.y = cvt_pk_bf16(v0[2], v0[3]); w.z = cvt_pk_bf16(v1[0], v1[1]); w.w = cvt_pk_bf16(v1[2], v1[3]);
;                     *(GAS u32x4*)(rowp + bj * HALF) = w; } }
.LBB0_1485:
	s_add_u32 s10, s10, 0x2a600000
	s_addc_u32 s11, s11, 0
	s_lshl_b64 s[22:23], s[56:57], 2
	s_waitcnt lgkmcnt(0)
	s_add_u32 s18, s18, s22
	s_addc_u32 s19, s19, s23
	s_lshl_b32 s9, s9, 5
	s_and_b32 s27, s9, 0x60
	s_add_i32 m0, s45, 0x18000
	v_lshl_add_u64 v[2:3], v[2:3], 0, s[14:15]
	s_lshl_b32 s26, s25, 13
	s_lshl_b32 s34, s27, 7
	s_waitcnt vmcnt(2)
	s_barrier
	global_load_lds_dwordx4 v[2:3], off
	v_lshl_add_u64 v[2:3], v[4:5], 0, s[14:15]
	s_add_i32 m0, s45, 0x1a000
	s_add_i32 s56, s45, 0x8000
	s_add_i32 s62, s45, 0xa000
	global_load_lds_dwordx4 v[2:3], off
	v_lshl_add_u64 v[2:3], v[6:7], 0, s[14:15]
	s_mov_b32 m0, s56
	s_add_u32 s22, s42, 0x80080
	global_load_lds_dwordx4 v[2:3], off
	v_lshl_add_u64 v[2:3], v[8:9], 0, s[14:15]
	s_mov_b32 m0, s62
	s_addc_u32 s23, s43, 0
	global_load_lds_dwordx4 v[2:3], off
	s_add_i32 m0, s45, 0x1c000
	v_lshl_add_u64 v[2:3], s[22:23], 0, v[202:203]
	global_load_lds_dwordx4 v[2:3], off
	v_lshl_add_u64 v[2:3], s[22:23], 0, v[150:151]
	s_add_i32 m0, s45, 0x1e000
	s_cmp_lg_u64 s[18:19], 0
	global_load_lds_dwordx4 v[2:3], off
	v_lshrrev_b32_e32 v3, 1, v0
	v_and_b32_e32 v3, 24, v3
	v_and_b32_e32 v2, 15, v0
	v_lshlrev_b32_e32 v4, 1, v3
	v_lshl_or_b32 v1, s25, 6, v2
	v_lshl_or_b32 v2, v2, 6, v4
	v_lshlrev_b32_e32 v4, 2, v0
	v_and_b32_e32 v4, 32, v4
	v_bitop3_b32 v5, v2, s26, v4 bitop3:0xde
	v_bitop3_b32 v160, s34, v2, v4 bitop3:0xf6
	v_lshlrev_b32_e32 v2, 15, v13
	v_and_b32_e32 v2, 0xffff0000, v2
	v_or_b32_e32 v161, s27, v3
	v_lshl_add_u32 v2, v14, 12, v2
	v_and_b32_e32 v3, 1, v13
	v_lshl_or_b32 v2, v3, 6, v2
	v_lshl_add_u32 v152, v15, 1, v2
	v_lshlrev_b32_e32 v2, 15, v10
	v_and_b32_e32 v2, 0xffff0000, v2
	s_waitcnt vmcnt(6)
	v_lshl_add_u32 v2, v11, 12, v2
	v_and_b32_e32 v3, 1, v10
	v_lshl_or_b32 v2, v3, 6, v2
	s_sext_i32_i16 s64, s24
	s_mov_b32 s9, s57
	s_cselect_b64 s[22:23], -1, 0
	v_mov_b32_e32 v153, v203
	v_lshl_add_u32 v154, v12, 1, v2
	v_mov_b32_e32 v155, v203
	s_mov_b32 s63, 0
	v_add_u32_e32 v162, 0, v5
	s_barrier
	s_mov_b32 s100, 0
	s_branch .LBB0_1487
.LBB0_1486:
	v_lshl_add_u32 v158, s44, 8, v1
	v_pk_add_f32 v[122:123], v[122:123], v[232:233]
	v_ashrrev_i32_e32 v159, 31, v158
	v_pk_add_f32 v[126:127], v[126:127], v[228:229]
	v_pk_add_f32 v[124:125], v[124:125], v[234:235]
	v_max_f32_e32 v122, 0, v122
	v_lshlrev_b64 v[164:165], 14, v[158:159]
	v_pk_add_f32 v[128:129], v[128:129], v[230:231]
	v_mul_f32_e32 v159, v122, v122
	v_max_f32_e32 v122, 0, v127
	v_max_f32_e32 v123, 0, v123
	v_max_f32_e32 v124, 0, v124
	v_lshl_add_u64 v[164:165], s[10:11], 0, v[164:165]
	v_lshlrev_b64 v[166:167], 1, v[156:157]
	v_max_f32_e32 v126, 0, v126
	v_mul_f32_e32 v122, v122, v122
	v_mul_f32_e32 v127, v123, v123
	v_max_f32_e32 v123, 0, v128
	v_mul_f32_e32 v128, v124, v124
	v_max_f32_e32 v124, 0, v129
	v_max_f32_e32 v125, 0, v125
	v_pk_add_f32 v[114:115], v[114:115], v[240:241]
	v_lshl_add_u64 v[156:157], v[164:165], 0, v[166:167]
	v_mul_f32_e32 v126, v126, v126
	v_mul_f32_e32 v123, v123, v123
	v_mul_f32_e32 v124, v124, v124
	v_mul_f32_e32 v125, v125, v125
	v_cvt_pk_bf16_f32 v122, v126, v122
	v_pk_add_f32 v[118:119], v[118:119], v[236:237]
	v_pk_add_f32 v[116:117], v[116:117], v[242:243]
	v_max_f32_e32 v114, 0, v114
	v_cvt_pk_bf16_f32 v123, v123, v124
	v_cvt_pk_bf16_f32 v124, v159, v127
	v_cvt_pk_bf16_f32 v125, v128, v125
	global_store_dwordx4 v[156:157], v[122:125], off
	v_pk_add_f32 v[120:121], v[120:121], v[238:239]
	v_max_f32_e32 v115, 0, v115
	v_mul_f32_e32 v122, v114, v114
	v_max_f32_e32 v114, 0, v119
	v_max_f32_e32 v116, 0, v116
	v_max_f32_e32 v118, 0, v118
	v_mul_f32_e32 v114, v114, v114
	v_mul_f32_e32 v119, v115, v115
	v_max_f32_e32 v115, 0, v120
	v_mul_f32_e32 v120, v116, v116
	v_max_f32_e32 v116, 0, v121
	v_max_f32_e32 v117, 0, v117
	v_mul_f32_e32 v118, v118, v118
	v_mul_f32_e32 v115, v115, v115
	v_mul_f32_e32 v116, v116, v116
	v_mul_f32_e32 v117, v117, v117
	v_cvt_pk_bf16_f32 v114, v118, v114
	v_cvt_pk_bf16_f32 v115, v115, v116
	v_cvt_pk_bf16_f32 v116, v122, v119
	v_cvt_pk_bf16_f32 v117, v120, v117
	global_store_dwordx4 v[156:157], v[114:117], off offset:256
	v_pk_add_f32 v[106:107], v[106:107], v[232:233]
	v_pk_add_f32 v[110:111], v[110:111], v[228:229]
	v_or_b32_e32 v114, 16, v158
	v_ashrrev_i32_e32 v115, 31, v114
	v_pk_add_f32 v[108:109], v[108:109], v[234:235]
	v_max_f32_e32 v106, 0, v106
	v_lshlrev_b64 v[114:115], 14, v[114:115]
	v_pk_add_f32 v[112:113], v[112:113], v[230:231]
	v_mul_f32_e32 v116, v106, v106
	v_max_f32_e32 v106, 0, v111
	v_max_f32_e32 v107, 0, v107
	v_max_f32_e32 v108, 0, v108
	v_lshl_add_u64 v[114:115], s[10:11], 0, v[114:115]
	v_max_f32_e32 v110, 0, v110
	v_mul_f32_e32 v106, v106, v106
	v_mul_f32_e32 v111, v107, v107
	v_max_f32_e32 v107, 0, v112
	v_mul_f32_e32 v112, v108, v108
	v_max_f32_e32 v108, 0, v113
	v_max_f32_e32 v109, 0, v109
	v_pk_add_f32 v[98:99], v[98:99], v[240:241]
	v_lshl_add_u64 v[114:115], v[114:115], 0, v[166:167]
	v_mul_f32_e32 v110, v110, v110
	v_mul_f32_e32 v107, v107, v107
	v_mul_f32_e32 v108, v108, v108
	v_mul_f32_e32 v109, v109, v109
	v_cvt_pk_bf16_f32 v106, v110, v106
	v_pk_add_f32 v[102:103], v[102:103], v[236:237]
	v_pk_add_f32 v[100:101], v[100:101], v[242:243]
	v_max_f32_e32 v98, 0, v98
	v_cvt_pk_bf16_f32 v107, v107, v108
	v_cvt_pk_bf16_f32 v108, v116, v111
	v_cvt_pk_bf16_f32 v109, v112, v109
	global_store_dwordx4 v[114:115], v[106:109], off
	v_pk_add_f32 v[104:105], v[104:105], v[238:239]
	v_max_f32_e32 v99, 0, v99
	v_mul_f32_e32 v106, v98, v98
	v_max_f32_e32 v98, 0, v103
	v_max_f32_e32 v100, 0, v100
	v_max_f32_e32 v102, 0, v102
	v_mul_f32_e32 v98, v98, v98
	v_mul_f32_e32 v103, v99, v99
	v_max_f32_e32 v99, 0, v104
	v_mul_f32_e32 v104, v100, v100
; #define GAS __attribute__((address_space(1)))
; __device__ __forceinline__ unsigned cvt_pk_bf16(float lo, float hi) { unsigned r; asm volatile("v_cvt_pk_bf16_f32 %0, %1, %2" : "=v"(r) : "v"(lo), "v"(hi)); return r; }
;     __device__ __forceinline__ void operator()(const f32x4 (&acc)[2][2][4][2], const Unit& u, int wr, int wc, int fr, int fq) const { base(acc, u, wr, wc, fr, fq); }
;     __device__ __forceinline__ void operator()(const f32x4 (&acc)[2][2][4][2], const Unit& u, int wr, int wc, int fr, int fq) const {
;         const int row0 = u.pm * BM + wr * 64 + fr, col0 = u.pn * BM + wc * 32 + 8 * fq;
;         f32x4 bv[2][2];
; #pragma unroll
;         for (int bj = 0; bj < 2; ++bj)
; #pragma unroll
;             for (int n = 0; n < 2; ++n) bv[bj][n] = bias ? *(const GAS f32x4*)(bias + col0 + bj * HALF + 4 * n) : (f32x4){0.f, 0.f, 0.f, 0.f};
; #pragma unroll
;         for (int ai = 0; ai < 2; ++ai)
; #pragma unroll
;             for (int m = 0; m < 4; ++m) { GAS bf16_t* rowp = O + (size_t)(row0 + ai * HALF + m * 16) * ldc + col0;
; #pragma unroll
;                 for (int bj = 0; bj < 2; ++bj) { f32x4 v0 = acc[ai][bj][m][0] + bv[bj][0], v1 = acc[ai][bj][m][1] + bv[bj][1];
;                     if (ACT == 1) {
; #pragma unroll
;                         for (int j = 0; j < 4; ++j) { const float a = fmaxf(v0[j], 0.f), b = fmaxf(v1[j], 0.f); v0[j] = a * a; v1[j] = b * b; } }
;                     u32x4 w; w.x = cvt_pk_bf16(v0[0], v0[1]); w.y = cvt_pk_bf16(v0[2], v0[3]); w.z = cvt_pk_bf16(v1[0], v1[1]); w.w = cvt_pk_bf16(v1[2], v1[3]);
;                     *(GAS u32x4*)(rowp + bj * HALF) = w; } }
	v_max_f32_e32 v100, 0, v105
	v_max_f32_e32 v101, 0, v101
	v_mul_f32_e32 v102, v102, v102
	v_mul_f32_e32 v99, v99, v99
	v_mul_f32_e32 v100, v100, v100
	v_mul_f32_e32 v101, v101, v101
	v_cvt_pk_bf16_f32 v98, v102, v98
	v_cvt_pk_bf16_f32 v99, v99, v100
	v_cvt_pk_bf16_f32 v100, v106, v103
	v_cvt_pk_bf16_f32 v101, v104, v101
	global_store_dwordx4 v[114:115], v[98:101], off offset:256
	v_pk_add_f32 v[90:91], v[90:91], v[232:233]
	v_pk_add_f32 v[94:95], v[94:95], v[228:229]
	v_or_b32_e32 v98, 32, v158
	v_ashrrev_i32_e32 v99, 31, v98
	v_pk_add_f32 v[92:93], v[92:93], v[234:235]
	v_max_f32_e32 v90, 0, v90
	v_lshlrev_b64 v[98:99], 14, v[98:99]
	v_pk_add_f32 v[96:97], v[96:97], v[230:231]
	v_mul_f32_e32 v100, v90, v90
	v_max_f32_e32 v90, 0, v95
	v_max_f32_e32 v91, 0, v91
	v_max_f32_e32 v92, 0, v92
	v_lshl_add_u64 v[98:99], s[10:11], 0, v[98:99]
	v_max_f32_e32 v94, 0, v94
	v_mul_f32_e32 v90, v90, v90
	v_mul_f32_e32 v95, v91, v91
	v_max_f32_e32 v91, 0, v96
	v_mul_f32_e32 v96, v92, v92
	v_max_f32_e32 v92, 0, v97
	v_max_f32_e32 v93, 0, v93
	v_pk_add_f32 v[82:83], v[82:83], v[240:241]
	v_lshl_add_u64 v[98:99], v[98:99], 0, v[166:167]
	v_mul_f32_e32 v94, v94, v94
	v_mul_f32_e32 v91, v91, v91
	v_mul_f32_e32 v92, v92, v92
	v_mul_f32_e32 v93, v93, v93
	v_cvt_pk_bf16_f32 v90, v94, v90
	v_pk_add_f32 v[86:87], v[86:87], v[236:237]
	v_pk_add_f32 v[84:85], v[84:85], v[242:243]
	v_max_f32_e32 v82, 0, v82
	v_cvt_pk_bf16_f32 v91, v91, v92
	v_cvt_pk_bf16_f32 v92, v100, v95
	v_cvt_pk_bf16_f32 v93, v96, v93
	global_store_dwordx4 v[98:99], v[90:93], off
	v_pk_add_f32 v[88:89], v[88:89], v[238:239]
	v_max_f32_e32 v83, 0, v83
	v_mul_f32_e32 v90, v82, v82
	v_max_f32_e32 v82, 0, v87
	v_max_f32_e32 v84, 0, v84
	v_max_f32_e32 v86, 0, v86
	v_mul_f32_e32 v82, v82, v82
	v_mul_f32_e32 v87, v83, v83
	v_max_f32_e32 v83, 0, v88
	v_mul_f32_e32 v88, v84, v84
	v_max_f32_e32 v84, 0, v89
	v_max_f32_e32 v85, 0, v85
	v_mul_f32_e32 v86, v86, v86
	v_mul_f32_e32 v83, v83, v83
	v_mul_f32_e32 v84, v84, v84
	v_mul_f32_e32 v85, v85, v85
	v_cvt_pk_bf16_f32 v82, v86, v82
	v_cvt_pk_bf16_f32 v83, v83, v84
	v_cvt_pk_bf16_f32 v84, v90, v87
	v_cvt_pk_bf16_f32 v85, v88, v85
	global_store_dwordx4 v[98:99], v[82:85], off offset:256
	v_pk_add_f32 v[74:75], v[74:75], v[232:233]
	v_pk_add_f32 v[78:79], v[78:79], v[228:229]
	v_or_b32_e32 v82, 48, v158
	v_ashrrev_i32_e32 v83, 31, v82
	v_pk_add_f32 v[76:77], v[76:77], v[234:235]
	v_max_f32_e32 v74, 0, v74
	v_lshlrev_b64 v[82:83], 14, v[82:83]
	v_pk_add_f32 v[80:81], v[80:81], v[230:231]
	v_mul_f32_e32 v84, v74, v74
	v_max_f32_e32 v74, 0, v79
	v_max_f32_e32 v75, 0, v75
	v_max_f32_e32 v76, 0, v76
	v_lshl_add_u64 v[82:83], s[10:11], 0, v[82:83]
	v_max_f32_e32 v78, 0, v78
	v_mul_f32_e32 v74, v74, v74
	v_mul_f32_e32 v79, v75, v75
	v_max_f32_e32 v75, 0, v80
	v_mul_f32_e32 v80, v76, v76
	v_max_f32_e32 v76, 0, v81
	v_max_f32_e32 v77, 0, v77
	v_pk_add_f32 v[68:69], v[68:69], v[242:243]
	v_pk_add_f32 v[66:67], v[66:67], v[240:241]
	v_lshl_add_u64 v[82:83], v[82:83], 0, v[166:167]
	v_mul_f32_e32 v78, v78, v78
	v_mul_f32_e32 v75, v75, v75
	v_mul_f32_e32 v76, v76, v76
	v_mul_f32_e32 v77, v77, v77
	v_cvt_pk_bf16_f32 v74, v78, v74
	v_pk_add_f32 v[72:73], v[72:73], v[238:239]
	v_pk_add_f32 v[70:71], v[70:71], v[236:237]
	v_max_f32_e32 v66, 0, v66
	v_max_f32_e32 v67, 0, v67
	v_max_f32_e32 v68, 0, v68
	v_cvt_pk_bf16_f32 v75, v75, v76
	v_cvt_pk_bf16_f32 v76, v84, v79
	v_cvt_pk_bf16_f32 v77, v80, v77
	global_store_dwordx4 v[82:83], v[74:77], off
	v_max_f32_e32 v70, 0, v70
	v_max_f32_e32 v69, 0, v69
	v_mul_f32_e32 v74, v66, v66
	v_max_f32_e32 v66, 0, v71
	v_mul_f32_e32 v71, v67, v67
	v_max_f32_e32 v67, 0, v72
	v_mul_f32_e32 v72, v68, v68
	v_max_f32_e32 v68, 0, v73
	v_mul_f32_e32 v66, v66, v66
	v_mul_f32_e32 v67, v67, v67
	v_mul_f32_e32 v68, v68, v68
	v_pk_add_f32 v[58:59], v[58:59], v[232:233]
	v_mul_f32_e32 v70, v70, v70
	v_mul_f32_e32 v69, v69, v69
	v_cvt_pk_bf16_f32 v66, v70, v66
	v_cvt_pk_bf16_f32 v67, v67, v68
	v_cvt_pk_bf16_f32 v68, v74, v71
	v_pk_add_f32 v[62:63], v[62:63], v[228:229]
	v_pk_add_f32 v[60:61], v[60:61], v[234:235]
	v_max_f32_e32 v58, 0, v58
	v_cvt_pk_bf16_f32 v69, v72, v69
	global_store_dwordx4 v[82:83], v[66:69], off offset:256
	v_pk_add_f32 v[64:65], v[64:65], v[230:231]
	v_max_f32_e32 v62, 0, v62
	v_mul_f32_e32 v68, v58, v58
	v_max_f32_e32 v58, 0, v63
	v_max_f32_e32 v59, 0, v59
	v_max_f32_e32 v60, 0, v60
	v_mul_f32_e32 v62, v62, v62
	v_mul_f32_e32 v58, v58, v58
	v_mul_f32_e32 v63, v59, v59
	v_max_f32_e32 v59, 0, v64
	v_mul_f32_e32 v64, v60, v60
	v_max_f32_e32 v60, 0, v65
	s_mov_b32 s25, 0x200000
	v_mul_f32_e32 v59, v59, v59
	v_max_f32_e32 v61, 0, v61
	v_mul_f32_e32 v60, v60, v60
	v_cvt_pk_bf16_f32 v58, v62, v58
	v_add_co_u32_e32 v62, vcc, s25, v156
	v_pk_add_f32 v[52:53], v[52:53], v[242:243]
	v_pk_add_f32 v[50:51], v[50:51], v[240:241]
	v_mul_f32_e32 v61, v61, v61
	v_cvt_pk_bf16_f32 v59, v59, v60
	v_cvt_pk_bf16_f32 v60, v68, v63
	v_addc_co_u32_e32 v63, vcc, 0, v157, vcc
	v_pk_add_f32 v[56:57], v[56:57], v[238:239]
	v_pk_add_f32 v[54:55], v[54:55], v[236:237]
	v_max_f32_e32 v50, 0, v50
	v_max_f32_e32 v51, 0, v51
	v_max_f32_e32 v52, 0, v52
	v_cvt_pk_bf16_f32 v61, v64, v61
	global_store_dwordx4 v[62:63], v[58:61], off
	s_mov_b64 s[42:43], 0x200000
	v_max_f32_e32 v54, 0, v54
	v_mul_f32_e32 v58, v50, v50
	v_max_f32_e32 v50, 0, v55
	v_mul_f32_e32 v55, v51, v51
	v_max_f32_e32 v51, 0, v56
	v_mul_f32_e32 v56, v52, v52
	v_max_f32_e32 v52, 0, v57
	v_mul_f32_e32 v50, v50, v50
	v_mul_f32_e32 v51, v51, v51
	v_max_f32_e32 v53, 0, v53
	v_mul_f32_e32 v52, v52, v52
	v_pk_add_f32 v[42:43], v[42:43], v[232:233]
	v_lshl_add_u64 v[66:67], v[156:157], 0, s[42:43]
; #define GAS __attribute__((address_space(1)))
; __device__ __forceinline__ unsigned cvt_pk_bf16(float lo, float hi) { unsigned r; asm volatile("v_cvt_pk_bf16_f32 %0, %1, %2" : "=v"(r) : "v"(lo), "v"(hi)); return r; }
;     __device__ __forceinline__ void operator()(const f32x4 (&acc)[2][2][4][2], const Unit& u, int wr, int wc, int fr, int fq) const { base(acc, u, wr, wc, fr, fq); }
;     __device__ __forceinline__ void operator()(const f32x4 (&acc)[2][2][4][2], const Unit& u, int wr, int wc, int fr, int fq) const {
;         const int row0 = u.pm * BM + wr * 64 + fr, col0 = u.pn * BM + wc * 32 + 8 * fq;
;         f32x4 bv[2][2];
; #pragma unroll
;         for (int bj = 0; bj < 2; ++bj)
; #pragma unroll
;             for (int n = 0; n < 2; ++n) bv[bj][n] = bias ? *(const GAS f32x4*)(bias + col0 + bj * HALF + 4 * n) : (f32x4){0.f, 0.f, 0.f, 0.f};
; #pragma unroll
;         for (int ai = 0; ai < 2; ++ai)
; #pragma unroll
;             for (int m = 0; m < 4; ++m) { GAS bf16_t* rowp = O + (size_t)(row0 + ai * HALF + m * 16) * ldc + col0;
; #pragma unroll
;                 for (int bj = 0; bj < 2; ++bj) { f32x4 v0 = acc[ai][bj][m][0] + bv[bj][0], v1 = acc[ai][bj][m][1] + bv[bj][1];
;                     if (ACT == 1) {
; #pragma unroll
;                         for (int j = 0; j < 4; ++j) { const float a = fmaxf(v0[j], 0.f), b = fmaxf(v1[j], 0.f); v0[j] = a * a; v1[j] = b * b; } }
;                     u32x4 w; w.x = cvt_pk_bf16(v0[0], v0[1]); w.y = cvt_pk_bf16(v0[2], v0[3]); w.z = cvt_pk_bf16(v1[0], v1[1]); w.w = cvt_pk_bf16(v1[2], v1[3]);
;                     *(GAS u32x4*)(rowp + bj * HALF) = w; } }
	v_mul_f32_e32 v54, v54, v54
	v_mul_f32_e32 v53, v53, v53
	v_cvt_pk_bf16_f32 v50, v54, v50
	v_cvt_pk_bf16_f32 v51, v51, v52
	v_cvt_pk_bf16_f32 v52, v58, v55
	v_pk_add_f32 v[46:47], v[46:47], v[228:229]
	v_pk_add_f32 v[44:45], v[44:45], v[234:235]
	v_max_f32_e32 v42, 0, v42
	v_cvt_pk_bf16_f32 v53, v56, v53
	global_store_dwordx4 v[66:67], v[50:53], off offset:256
	v_pk_add_f32 v[48:49], v[48:49], v[230:231]
	v_max_f32_e32 v46, 0, v46
	v_mul_f32_e32 v52, v42, v42
	v_max_f32_e32 v42, 0, v47
	v_max_f32_e32 v43, 0, v43
	v_max_f32_e32 v44, 0, v44
	v_mul_f32_e32 v46, v46, v46
	v_mul_f32_e32 v42, v42, v42
	v_mul_f32_e32 v47, v43, v43
	v_max_f32_e32 v43, 0, v48
	v_mul_f32_e32 v48, v44, v44
	v_max_f32_e32 v44, 0, v49
	s_mov_b32 s25, 0x240000
	v_mul_f32_e32 v43, v43, v43
	v_max_f32_e32 v45, 0, v45
	v_mul_f32_e32 v44, v44, v44
	v_cvt_pk_bf16_f32 v42, v46, v42
	v_add_co_u32_e32 v46, vcc, s25, v156
	v_pk_add_f32 v[36:37], v[36:37], v[242:243]
	v_pk_add_f32 v[34:35], v[34:35], v[240:241]
	v_mul_f32_e32 v45, v45, v45
	v_cvt_pk_bf16_f32 v43, v43, v44
	v_cvt_pk_bf16_f32 v44, v52, v47
	v_addc_co_u32_e32 v47, vcc, 0, v157, vcc
	v_pk_add_f32 v[40:41], v[40:41], v[238:239]
	v_pk_add_f32 v[38:39], v[38:39], v[236:237]
	v_max_f32_e32 v34, 0, v34
	v_max_f32_e32 v35, 0, v35
	v_max_f32_e32 v36, 0, v36
	v_cvt_pk_bf16_f32 v45, v48, v45
	global_store_dwordx4 v[46:47], v[42:45], off
	s_mov_b64 s[42:43], 0x240000
	v_max_f32_e32 v38, 0, v38
	v_mul_f32_e32 v42, v34, v34
	v_max_f32_e32 v34, 0, v39
	v_mul_f32_e32 v39, v35, v35
	v_max_f32_e32 v35, 0, v40
	v_mul_f32_e32 v40, v36, v36
	v_max_f32_e32 v36, 0, v41
	v_mul_f32_e32 v34, v34, v34
	v_mul_f32_e32 v35, v35, v35
	v_max_f32_e32 v37, 0, v37
	v_mul_f32_e32 v36, v36, v36
	v_pk_add_f32 v[26:27], v[26:27], v[232:233]
	v_lshl_add_u64 v[50:51], v[156:157], 0, s[42:43]
	v_mul_f32_e32 v38, v38, v38
	v_mul_f32_e32 v37, v37, v37
	v_cvt_pk_bf16_f32 v34, v38, v34
	v_cvt_pk_bf16_f32 v35, v35, v36
	v_cvt_pk_bf16_f32 v36, v42, v39
	v_pk_add_f32 v[30:31], v[30:31], v[228:229]
	v_pk_add_f32 v[28:29], v[28:29], v[234:235]
	v_max_f32_e32 v26, 0, v26
	v_cvt_pk_bf16_f32 v37, v40, v37
	global_store_dwordx4 v[50:51], v[34:37], off offset:256
	v_pk_add_f32 v[32:33], v[32:33], v[230:231]
	v_max_f32_e32 v30, 0, v30
	v_mul_f32_e32 v36, v26, v26
	v_max_f32_e32 v26, 0, v31
	v_max_f32_e32 v27, 0, v27
	v_max_f32_e32 v28, 0, v28
	v_mul_f32_e32 v30, v30, v30
	v_mul_f32_e32 v26, v26, v26
	v_mul_f32_e32 v31, v27, v27
	v_max_f32_e32 v27, 0, v32
	v_mul_f32_e32 v32, v28, v28
	v_max_f32_e32 v28, 0, v33
	s_mov_b32 s25, 0x280000
	v_mul_f32_e32 v27, v27, v27
	v_max_f32_e32 v29, 0, v29
	v_mul_f32_e32 v28, v28, v28
	v_cvt_pk_bf16_f32 v26, v30, v26
	v_add_co_u32_e32 v30, vcc, s25, v156
	v_pk_add_f32 v[20:21], v[20:21], v[242:243]
	v_pk_add_f32 v[18:19], v[18:19], v[240:241]
	v_mul_f32_e32 v29, v29, v29
	v_cvt_pk_bf16_f32 v27, v27, v28
	v_cvt_pk_bf16_f32 v28, v36, v31
	v_addc_co_u32_e32 v31, vcc, 0, v157, vcc
	v_pk_add_f32 v[24:25], v[24:25], v[238:239]
	v_pk_add_f32 v[22:23], v[22:23], v[236:237]
	v_max_f32_e32 v18, 0, v18
	v_max_f32_e32 v19, 0, v19
	v_max_f32_e32 v20, 0, v20
	v_cvt_pk_bf16_f32 v29, v32, v29
	global_store_dwordx4 v[30:31], v[26:29], off
	s_mov_b64 s[42:43], 0x280000
	v_max_f32_e32 v22, 0, v22
	v_mul_f32_e32 v26, v18, v18
	v_max_f32_e32 v18, 0, v23
	v_mul_f32_e32 v23, v19, v19
	v_max_f32_e32 v19, 0, v24
	v_mul_f32_e32 v24, v20, v20
	v_max_f32_e32 v20, 0, v25
	v_mul_f32_e32 v18, v18, v18
	v_mul_f32_e32 v19, v19, v19
	v_max_f32_e32 v21, 0, v21
	v_mul_f32_e32 v20, v20, v20
	v_pk_add_f32 v[10:11], v[10:11], v[232:233]
	v_lshl_add_u64 v[34:35], v[156:157], 0, s[42:43]
	v_mul_f32_e32 v22, v22, v22
	v_mul_f32_e32 v21, v21, v21
	v_cvt_pk_bf16_f32 v18, v22, v18
	v_cvt_pk_bf16_f32 v19, v19, v20
	v_cvt_pk_bf16_f32 v20, v26, v23
	v_pk_add_f32 v[14:15], v[14:15], v[228:229]
	v_pk_add_f32 v[12:13], v[12:13], v[234:235]
	v_max_f32_e32 v10, 0, v10
	v_cvt_pk_bf16_f32 v21, v24, v21
	global_store_dwordx4 v[34:35], v[18:21], off offset:256
	v_pk_add_f32 v[16:17], v[16:17], v[230:231]
	v_max_f32_e32 v14, 0, v14
	v_mul_f32_e32 v20, v10, v10
	v_max_f32_e32 v10, 0, v15
	v_max_f32_e32 v11, 0, v11
	v_max_f32_e32 v12, 0, v12
	v_mul_f32_e32 v14, v14, v14
	v_mul_f32_e32 v10, v10, v10
	v_mul_f32_e32 v15, v11, v11
	v_max_f32_e32 v11, 0, v16
	v_mul_f32_e32 v16, v12, v12
	v_max_f32_e32 v12, 0, v17
	s_mov_b32 s25, 0x2c0000
	v_mul_f32_e32 v11, v11, v11
	v_max_f32_e32 v13, 0, v13
	v_mul_f32_e32 v12, v12, v12
	v_cvt_pk_bf16_f32 v10, v14, v10
	v_add_co_u32_e32 v14, vcc, s25, v156
	v_pk_add_f32 v[4:5], v[4:5], v[242:243]
	v_pk_add_f32 v[2:3], v[2:3], v[240:241]
	v_mul_f32_e32 v13, v13, v13
	v_cvt_pk_bf16_f32 v11, v11, v12
	v_cvt_pk_bf16_f32 v12, v20, v15
	v_addc_co_u32_e32 v15, vcc, 0, v157, vcc
	v_pk_add_f32 v[8:9], v[8:9], v[238:239]
	v_pk_add_f32 v[6:7], v[6:7], v[236:237]
	v_max_f32_e32 v2, 0, v2
	v_max_f32_e32 v3, 0, v3
	v_max_f32_e32 v4, 0, v4
	s_mov_b64 s[42:43], 0x2c0000
	v_cvt_pk_bf16_f32 v13, v16, v13
	global_store_dwordx4 v[14:15], v[10:13], off
	v_max_f32_e32 v5, 0, v5
	v_lshl_add_u64 v[18:19], v[156:157], 0, s[42:43]
	v_mul_f32_e32 v10, v2, v2
	v_max_f32_e32 v2, 0, v7
	v_mul_f32_e32 v7, v3, v3
	v_max_f32_e32 v3, 0, v8
	v_mul_f32_e32 v8, v4, v4
	v_max_f32_e32 v4, 0, v9
	v_max_f32_e32 v6, 0, v6
	v_mul_f32_e32 v2, v2, v2
	v_mul_f32_e32 v3, v3, v3
	v_mul_f32_e32 v4, v4, v4
	v_mul_f32_e32 v5, v5, v5
	s_and_b64 vcc, exec, s[40:41]
	s_mov_b32 s64, s24
	s_mov_b32 s44, s26
	s_mov_b64 s[42:43], s[38:39]
	s_mov_b64 s[46:47], s[34:35]
	v_mul_f32_e32 v6, v6, v6
	v_cvt_pk_bf16_f32 v2, v6, v2
	v_cvt_pk_bf16_f32 v3, v3, v4
	v_cvt_pk_bf16_f32 v4, v10, v7
	v_cvt_pk_bf16_f32 v5, v8, v5
	global_store_dwordx4 v[18:19], v[2:5], off offset:256
	s_cbranch_vccnz .LBB0_1499
	s_mov_b32 s100, 1

; #define GAS __attribute__((address_space(1)))
; #define PG8_STAGE(bufoff, gbase, voff) do { _Pragma("unroll") for (int _i = 0; _i < 2; ++_i) \
;         __builtin_amdgcn_global_load_lds((const GAS unsigned*)((const GAS char*)(gbase) + (voff)[_i]), (LAS unsigned*)(lds + (bufoff) + ldsw + _i * 8192), 16, 0, 0); } while (0)
; #define PG8_LDA(dst, b, h) do { _Pragma("unroll") for (int m = 0; m < 4; ++m) _Pragma("unroll") for (int k = 0; k < 2; ++k) dst[m][k] = *(const LAS bf16x8*)(lds + PG8_SA(b, h) + aoff + m * 2048 + k * 1024); } while (0)
; #define PG8_LDB(dst, b, h) do { _Pragma("unroll") for (int n = 0; n < 2; ++n) _Pragma("unroll") for (int k = 0; k < 2; ++k) dst[n][k] = *(const LAS bf16x8*)(lds + PG8_SB(b, h) + boff + n * 2048 + k * 1024); } while (0)
; #define PG8_MMA(ai, bj, At, Bt) do { __builtin_amdgcn_sched_barrier(0); _Pragma("unroll") for (int m = 0; m < 4; ++m) _Pragma("unroll") for (int n = 0; n < 2; ++n) _Pragma("unroll") for (int k = 0; k < 2; ++k) \
;         acc[ai][bj][m][n] = __builtin_amdgcn_mfma_f32_16x16x32_bf16(Bt[n][k], At[m][k], acc[ai][bj][m][n], 0, 0, 0); __builtin_amdgcn_sched_barrier(0); } while (0)
; #define PG8_WAIT_V(n) asm volatile("s_waitcnt vmcnt(" #n ")" ::: "memory")
; #define PG8_BAR __builtin_amdgcn_s_barrier()
; template <class Epi, class Sched, bool ALIGN_EPI, bool SP2>
; __device__ __forceinline__ void gemm_phase(LAS unsigned char* lds, const int tid, const Gemm g, const Sched& S, const Epi& E) {
;     ...
;         for (int t = 0; t < nt; t += 2) {
;             const bool last = (t == nt - 2);
;             const GAS char* a1 = cA + (size_t)(t + 1) * kstep;
;             const GAS char* a2 = last ? nA : cA + (size_t)(t + 2) * kstep; const GAS char* b2 = last ? nB : cB + (size_t)(t + 2) * kstep;
;             const GAS char* a3 = a2 + kstep; const GAS char* b3 = b2 + kstep;
;             if constexpr (SP2) {
;             PG8_LDB(B0, 0, 0); PG8_LDB(B1, 0, 1); PG8_SCHED; PG8_LDA(At, 0, 0); PG8_STAGE(PG8_SA(1, 1), a1 + hstepA, voffA);
;             PG8_WAIT_V(8); PG8_WAIT_L(0); PG8_BAR; PG8_MMA(0, 0, At, B0); PG8_MMA(0, 1, At, B1); PG8_BAR; PG8_SCHED;
;             PG8_LDA(At, 0, 1); PG8_STAGE(PG8_SB(0, 0), b2, voffB); PG8_STAGE(PG8_SB(0, 1), b2 + hstepB, voffB); PG8_STAGE(PG8_SA(0, 0), a2, voffA);
;             PG8_WAIT_V(8); PG8_WAIT_L(0); PG8_BAR; PG8_MMA(1, 0, At, B0); PG8_MMA(1, 1, At, B1); PG8_BAR; PG8_SCHED;
.LBB0_1490:
	s_add_u32 s46, s42, 0xfff80080
	s_addc_u32 s47, s43, -1
	s_add_i32 s72, 0, 0x10000
	s_cmp_eq_u32 s71, 28
	s_cselect_b32 s49, s27, s47
	s_cselect_b32 s48, s65, s46
	s_cselect_b32 s47, s25, s70
	s_cselect_b32 s46, s68, s69
	s_add_i32 s82, 0, 0x14000
	v_add_u32_e32 v142, s72, v160
	v_add_u32_e32 v163, s82, v160
	ds_read_b128 v[130:133], v142
	ds_read_b128 v[134:137], v142 offset:1024
	ds_read_b128 v[138:141], v142 offset:2048
	ds_read_b128 v[142:145], v142 offset:3072
	ds_read_b128 v[156:159], v163
	ds_read_b128 v[164:167], v163 offset:1024
	ds_read_b128 v[168:171], v163 offset:2048
	ds_read_b128 v[172:175], v163 offset:3072
	v_lshl_add_u64 v[200:201], s[42:43], 0, v[154:155]
	s_add_i32 m0, s45, 0xc000
	ds_read_b128 v[176:179], v162
	ds_read_b128 v[180:183], v162 offset:1024
	ds_read_b128 v[184:187], v162 offset:2048
	ds_read_b128 v[188:191], v162 offset:3072
	ds_read_b128 v[192:195], v162 offset:4096
	ds_read_b128 v[196:199], v162 offset:5120
	ds_read_b128 v[214:217], v162 offset:6144
	ds_read_b128 v[218:221], v162 offset:7168
	global_load_lds_dwordx4 v[200:201], off
	v_lshl_add_u64 v[200:201], s[42:43], 0, v[152:153]
	s_add_i32 m0, s45, 0xe000
	s_nop 0
	global_load_lds_dwordx4 v[200:201], off
	s_cmp_lg_u32 s100, 0
	s_cbranch_scc1 .Lm1_rw1
	s_waitcnt vmcnt(8)
.Lm1_rj1:
	s_waitcnt lgkmcnt(0)
	s_barrier
	s_waitcnt lgkmcnt(0)
	v_mfma_f32_16x16x32_bf16 v[126:129], v[130:133], v[176:179], v[126:129]
	v_mfma_f32_16x16x32_bf16 v[122:125], v[138:141], v[176:179], v[122:125]
	v_mfma_f32_16x16x32_bf16 v[110:113], v[130:133], v[184:187], v[110:113]
	v_mfma_f32_16x16x32_bf16 v[106:109], v[138:141], v[184:187], v[106:109]
	v_mfma_f32_16x16x32_bf16 v[94:97], v[130:133], v[192:195], v[94:97]
	v_mfma_f32_16x16x32_bf16 v[90:93], v[138:141], v[192:195], v[90:93]
	v_mfma_f32_16x16x32_bf16 v[78:81], v[130:133], v[214:217], v[78:81]
	v_mfma_f32_16x16x32_bf16 v[74:77], v[138:141], v[214:217], v[74:77]
	v_mfma_f32_16x16x32_bf16 v[126:129], v[134:137], v[180:183], v[126:129]
	v_mfma_f32_16x16x32_bf16 v[122:125], v[142:145], v[180:183], v[122:125]
	v_mfma_f32_16x16x32_bf16 v[110:113], v[134:137], v[188:191], v[110:113]
	v_mfma_f32_16x16x32_bf16 v[106:109], v[142:145], v[188:191], v[106:109]
	v_mfma_f32_16x16x32_bf16 v[94:97], v[134:137], v[196:199], v[94:97]
	v_mfma_f32_16x16x32_bf16 v[90:93], v[142:145], v[196:199], v[90:93]
	v_mfma_f32_16x16x32_bf16 v[78:81], v[134:137], v[218:221], v[78:81]
	v_mfma_f32_16x16x32_bf16 v[74:77], v[142:145], v[218:221], v[74:77]
	v_mfma_f32_16x16x32_bf16 v[118:121], v[156:159], v[176:179], v[118:121]
	v_mfma_f32_16x16x32_bf16 v[114:117], v[168:171], v[176:179], v[114:117]
	v_mfma_f32_16x16x32_bf16 v[102:105], v[156:159], v[184:187], v[102:105]
	v_mfma_f32_16x16x32_bf16 v[98:101], v[168:171], v[184:187], v[98:101]
	v_mfma_f32_16x16x32_bf16 v[86:89], v[156:159], v[192:195], v[86:89]
	v_mfma_f32_16x16x32_bf16 v[82:85], v[168:171], v[192:195], v[82:85]
	v_mfma_f32_16x16x32_bf16 v[70:73], v[156:159], v[214:217], v[70:73]
	v_mfma_f32_16x16x32_bf16 v[66:69], v[168:171], v[214:217], v[66:69]
	v_mfma_f32_16x16x32_bf16 v[118:121], v[164:167], v[180:183], v[118:121]
	v_mfma_f32_16x16x32_bf16 v[114:117], v[172:175], v[180:183], v[114:117]
	v_mfma_f32_16x16x32_bf16 v[102:105], v[164:167], v[188:191], v[102:105]
	v_mfma_f32_16x16x32_bf16 v[98:101], v[172:175], v[188:191], v[98:101]
	v_mfma_f32_16x16x32_bf16 v[86:89], v[164:167], v[196:199], v[86:89]
	v_mfma_f32_16x16x32_bf16 v[82:85], v[172:175], v[196:199], v[82:85]
	v_mfma_f32_16x16x32_bf16 v[70:73], v[164:167], v[218:221], v[70:73]
	v_mfma_f32_16x16x32_bf16 v[66:69], v[172:175], v[218:221], v[66:69]
	s_barrier
	s_add_i32 s72, s72, s58
	v_lshl_add_u64 v[200:201], s[46:47], 0, v[202:203]
	s_mov_b32 m0, s72
	ds_read_b128 v[176:179], v162 offset:16384
	ds_read_b128 v[180:183], v162 offset:17408
	ds_read_b128 v[184:187], v162 offset:18432
	ds_read_b128 v[188:191], v162 offset:19456
	ds_read_b128 v[192:195], v162 offset:20480
	ds_read_b128 v[196:199], v162 offset:21504
	ds_read_b128 v[214:217], v162 offset:22528
	ds_read_b128 v[218:221], v162 offset:23552
	global_load_lds_dwordx4 v[200:201], off
	s_add_i32 m0, s72, 0x2000
	s_add_u32 s72, s46, 0x80000
	v_lshl_add_u64 v[222:223], s[46:47], 0, v[150:151]
	s_addc_u32 s73, s47, 0
	s_add_i32 s82, s82, s58
	global_load_lds_dwordx4 v[222:223], off
	v_lshl_add_u64 v[224:225], s[72:73], 0, v[202:203]
	s_mov_b32 m0, s82
	v_lshl_add_u64 v[226:227], s[48:49], 0, v[148:149]
	global_load_lds_dwordx4 v[224:225], off
	v_lshl_add_u64 v[224:225], s[72:73], 0, v[150:151]
	s_add_i32 m0, s82, 0x2000
	s_nop 0
	global_load_lds_dwordx4 v[224:225], off
	v_lshl_add_u64 v[224:225], s[48:49], 0, v[146:147]
	s_mov_b32 m0, s45
	s_nop 0
	global_load_lds_dwordx4 v[224:225], off
	s_mov_b32 m0, s59
	s_nop 0
	global_load_lds_dwordx4 v[226:227], off
	s_cmp_lg_u32 s100, 0
	s_cbranch_scc1 .Lm1_rw2
	s_waitcnt vmcnt(8)
; #define PG8_STAGE(bufoff, gbase, voff) do { _Pragma("unroll") for (int _i = 0; _i < 2; ++_i) \
;         __builtin_amdgcn_global_load_lds((const GAS unsigned*)((const GAS char*)(gbase) + (voff)[_i]), (LAS unsigned*)(lds + (bufoff) + ldsw + _i * 8192), 16, 0, 0); } while (0)
; #define PG8_LDA(dst, b, h) do { _Pragma("unroll") for (int m = 0; m < 4; ++m) _Pragma("unroll") for (int k = 0; k < 2; ++k) dst[m][k] = *(const LAS bf16x8*)(lds + PG8_SA(b, h) + aoff + m * 2048 + k * 1024); } while (0)
; #define PG8_LDB(dst, b, h) do { _Pragma("unroll") for (int n = 0; n < 2; ++n) _Pragma("unroll") for (int k = 0; k < 2; ++k) dst[n][k] = *(const LAS bf16x8*)(lds + PG8_SB(b, h) + boff + n * 2048 + k * 1024); } while (0)
; #define PG8_MMA(ai, bj, At, Bt) do { __builtin_amdgcn_sched_barrier(0); _Pragma("unroll") for (int m = 0; m < 4; ++m) _Pragma("unroll") for (int n = 0; n < 2; ++n) _Pragma("unroll") for (int k = 0; k < 2; ++k) \
;         acc[ai][bj][m][n] = __builtin_amdgcn_mfma_f32_16x16x32_bf16(Bt[n][k], At[m][k], acc[ai][bj][m][n], 0, 0, 0); __builtin_amdgcn_sched_barrier(0); } while (0)
; #define PG8_WAIT_V(n) asm volatile("s_waitcnt vmcnt(" #n ")" ::: "memory")
; #define PG8_WAIT_L(n) asm volatile("s_waitcnt lgkmcnt(" #n ")" ::: "memory")
; #define PG8_BAR __builtin_amdgcn_s_barrier()
; #define PG8_SCHED __builtin_amdgcn_sched_barrier(0)
; template <class Epi, class Sched, bool ALIGN_EPI, bool SP2>
; __device__ __forceinline__ void gemm_phase(LAS unsigned char* lds, const int tid, const Gemm g, const Sched& S, const Epi& E) {
;     ...
;             PG8_WAIT_V(8); PG8_WAIT_L(0); PG8_BAR; PG8_MMA(1, 0, At, B0); PG8_MMA(1, 1, At, B1); PG8_BAR; PG8_SCHED;
;             PG8_LDB(B0, 1, 0); PG8_LDB(B1, 1, 1); PG8_SCHED; PG8_LDA(At, 1, 0); PG8_STAGE(PG8_SA(0, 1), a2 + hstepA, voffA);
;             PG8_WAIT_V(8); PG8_WAIT_L(0); PG8_BAR; PG8_MMA(0, 0, At, B0); PG8_MMA(0, 1, At, B1); PG8_BAR; PG8_SCHED;
.Lm1_rj2:
	s_mov_b32 s100, 0
	s_waitcnt lgkmcnt(0)
	s_barrier
	s_waitcnt lgkmcnt(0)
	v_mfma_f32_16x16x32_bf16 v[62:65], v[130:133], v[176:179], v[62:65]
	v_mfma_f32_16x16x32_bf16 v[58:61], v[138:141], v[176:179], v[58:61]
	v_mfma_f32_16x16x32_bf16 v[46:49], v[130:133], v[184:187], v[46:49]
	v_mfma_f32_16x16x32_bf16 v[42:45], v[138:141], v[184:187], v[42:45]
	v_mfma_f32_16x16x32_bf16 v[30:33], v[130:133], v[192:195], v[30:33]
	v_mfma_f32_16x16x32_bf16 v[26:29], v[138:141], v[192:195], v[26:29]
	v_mfma_f32_16x16x32_bf16 v[14:17], v[130:133], v[214:217], v[14:17]
	v_mfma_f32_16x16x32_bf16 v[10:13], v[138:141], v[214:217], v[10:13]
	v_mfma_f32_16x16x32_bf16 v[62:65], v[134:137], v[180:183], v[62:65]
	v_mfma_f32_16x16x32_bf16 v[58:61], v[142:145], v[180:183], v[58:61]
	v_mfma_f32_16x16x32_bf16 v[46:49], v[134:137], v[188:191], v[46:49]
	v_mfma_f32_16x16x32_bf16 v[42:45], v[142:145], v[188:191], v[42:45]
	v_mfma_f32_16x16x32_bf16 v[30:33], v[134:137], v[196:199], v[30:33]
	v_mfma_f32_16x16x32_bf16 v[26:29], v[142:145], v[196:199], v[26:29]
	v_mfma_f32_16x16x32_bf16 v[14:17], v[134:137], v[218:221], v[14:17]
	v_mfma_f32_16x16x32_bf16 v[10:13], v[142:145], v[218:221], v[10:13]
	v_mfma_f32_16x16x32_bf16 v[54:57], v[156:159], v[176:179], v[54:57]
	v_mfma_f32_16x16x32_bf16 v[50:53], v[168:171], v[176:179], v[50:53]
	v_mfma_f32_16x16x32_bf16 v[38:41], v[156:159], v[184:187], v[38:41]
	v_mfma_f32_16x16x32_bf16 v[34:37], v[168:171], v[184:187], v[34:37]
	v_mfma_f32_16x16x32_bf16 v[22:25], v[156:159], v[192:195], v[22:25]
	v_mfma_f32_16x16x32_bf16 v[18:21], v[168:171], v[192:195], v[18:21]
	v_mfma_f32_16x16x32_bf16 v[6:9], v[156:159], v[214:217], v[6:9]
	v_mfma_f32_16x16x32_bf16 v[2:5], v[168:171], v[214:217], v[2:5]
	v_mfma_f32_16x16x32_bf16 v[54:57], v[164:167], v[180:183], v[54:57]
	v_mfma_f32_16x16x32_bf16 v[50:53], v[172:175], v[180:183], v[50:53]
	v_mfma_f32_16x16x32_bf16 v[38:41], v[164:167], v[188:191], v[38:41]
	v_mfma_f32_16x16x32_bf16 v[34:37], v[172:175], v[188:191], v[34:37]
	v_mfma_f32_16x16x32_bf16 v[22:25], v[164:167], v[196:199], v[22:25]
	v_mfma_f32_16x16x32_bf16 v[18:21], v[172:175], v[196:199], v[18:21]
	v_mfma_f32_16x16x32_bf16 v[6:9], v[164:167], v[218:221], v[6:9]
	v_mfma_f32_16x16x32_bf16 v[2:5], v[172:175], v[218:221], v[2:5]
	s_barrier
	s_add_i32 s72, 0, 0x18000
	s_add_i32 s73, 0, 0x1c000
	v_add_u32_e32 v142, s72, v160
	v_add_u32_e32 v163, s73, v160
	ds_read_b128 v[130:133], v142
	ds_read_b128 v[134:137], v142 offset:1024
	ds_read_b128 v[138:141], v142 offset:2048
	ds_read_b128 v[142:145], v142 offset:3072
	ds_read_b128 v[156:159], v163
	ds_read_b128 v[164:167], v163 offset:1024
	ds_read_b128 v[168:171], v163 offset:2048
	ds_read_b128 v[172:175], v163 offset:3072
	s_add_u32 s48, s48, 0x80000
	s_addc_u32 s49, s49, 0
	s_mov_b32 m0, s60
	v_lshl_add_u64 v[246:247], s[48:49], 0, v[146:147]
	ds_read_b128 v[176:179], v162 offset:32768
	ds_read_b128 v[180:183], v162 offset:33792
	ds_read_b128 v[184:187], v162 offset:34816
	ds_read_b128 v[188:191], v162 offset:35840
	ds_read_b128 v[192:195], v162 offset:36864
	ds_read_b128 v[196:199], v162 offset:37888
	ds_read_b128 v[214:217], v162 offset:38912
	ds_read_b128 v[218:221], v162 offset:39936
	global_load_lds_dwordx4 v[246:247], off
	v_lshl_add_u64 v[246:247], s[48:49], 0, v[148:149]
	s_mov_b32 m0, s61
	s_nop 0
	global_load_lds_dwordx4 v[246:247], off
	s_waitcnt vmcnt(8)
	s_waitcnt lgkmcnt(0)
	s_barrier
	s_waitcnt lgkmcnt(0)
	v_mfma_f32_16x16x32_bf16 v[126:129], v[130:133], v[176:179], v[126:129]
	v_mfma_f32_16x16x32_bf16 v[122:125], v[138:141], v[176:179], v[122:125]
	v_mfma_f32_16x16x32_bf16 v[110:113], v[130:133], v[184:187], v[110:113]
	v_mfma_f32_16x16x32_bf16 v[106:109], v[138:141], v[184:187], v[106:109]
	v_mfma_f32_16x16x32_bf16 v[94:97], v[130:133], v[192:195], v[94:97]
	v_mfma_f32_16x16x32_bf16 v[90:93], v[138:141], v[192:195], v[90:93]
	v_mfma_f32_16x16x32_bf16 v[78:81], v[130:133], v[214:217], v[78:81]
	v_mfma_f32_16x16x32_bf16 v[74:77], v[138:141], v[214:217], v[74:77]
	v_mfma_f32_16x16x32_bf16 v[126:129], v[134:137], v[180:183], v[126:129]
	v_mfma_f32_16x16x32_bf16 v[122:125], v[142:145], v[180:183], v[122:125]
	v_mfma_f32_16x16x32_bf16 v[110:113], v[134:137], v[188:191], v[110:113]
	v_mfma_f32_16x16x32_bf16 v[106:109], v[142:145], v[188:191], v[106:109]
	v_mfma_f32_16x16x32_bf16 v[94:97], v[134:137], v[196:199], v[94:97]
	v_mfma_f32_16x16x32_bf16 v[90:93], v[142:145], v[196:199], v[90:93]
	v_mfma_f32_16x16x32_bf16 v[78:81], v[134:137], v[218:221], v[78:81]
	v_mfma_f32_16x16x32_bf16 v[74:77], v[142:145], v[218:221], v[74:77]
	v_mfma_f32_16x16x32_bf16 v[118:121], v[156:159], v[176:179], v[118:121]
	v_mfma_f32_16x16x32_bf16 v[114:117], v[168:171], v[176:179], v[114:117]
	v_mfma_f32_16x16x32_bf16 v[102:105], v[156:159], v[184:187], v[102:105]
	v_mfma_f32_16x16x32_bf16 v[98:101], v[168:171], v[184:187], v[98:101]
	v_mfma_f32_16x16x32_bf16 v[86:89], v[156:159], v[192:195], v[86:89]
	v_mfma_f32_16x16x32_bf16 v[82:85], v[168:171], v[192:195], v[82:85]
	v_mfma_f32_16x16x32_bf16 v[70:73], v[156:159], v[214:217], v[70:73]
	v_mfma_f32_16x16x32_bf16 v[66:69], v[168:171], v[214:217], v[66:69]
	v_mfma_f32_16x16x32_bf16 v[118:121], v[164:167], v[180:183], v[118:121]
	v_mfma_f32_16x16x32_bf16 v[114:117], v[172:175], v[180:183], v[114:117]
	v_mfma_f32_16x16x32_bf16 v[102:105], v[164:167], v[188:191], v[102:105]
	v_mfma_f32_16x16x32_bf16 v[98:101], v[172:175], v[188:191], v[98:101]
	v_mfma_f32_16x16x32_bf16 v[86:89], v[164:167], v[196:199], v[86:89]
	v_mfma_f32_16x16x32_bf16 v[82:85], v[172:175], v[196:199], v[82:85]
	v_mfma_f32_16x16x32_bf16 v[70:73], v[164:167], v[218:221], v[70:73]
	v_mfma_f32_16x16x32_bf16 v[66:69], v[172:175], v[218:221], v[66:69]
	s_barrier
; #define PG8_STAGE(bufoff, gbase, voff) do { _Pragma("unroll") for (int _i = 0; _i < 2; ++_i) \
;         __builtin_amdgcn_global_load_lds((const GAS unsigned*)((const GAS char*)(gbase) + (voff)[_i]), (LAS unsigned*)(lds + (bufoff) + ldsw + _i * 8192), 16, 0, 0); } while (0)
; #define PG8_BAR __builtin_amdgcn_s_barrier()
; template <class Epi, class Sched, bool ALIGN_EPI, bool SP2>
; __device__ __forceinline__ void gemm_phase(LAS unsigned char* lds, const int tid, const Gemm g, const Sched& S, const Epi& E) {
;     ...
;             PG8_WAIT_V(8); PG8_WAIT_L(0); PG8_BAR; PG8_MMA(0, 0, At, B0); PG8_MMA(0, 1, At, B1); PG8_BAR; PG8_SCHED;
;             PG8_LDA(At, 1, 1); PG8_STAGE(PG8_SB(1, 0), b3, voffB); PG8_STAGE(PG8_SB(1, 1), b3 + hstepB, voffB); PG8_STAGE(PG8_SA(1, 0), a3, voffA);
;             PG8_WAIT_V(8); PG8_WAIT_L(0); PG8_BAR; PG8_MMA(1, 0, At, B0); PG8_MMA(1, 1, At, B1); PG8_BAR; PG8_SCHED;
;             } else {
;             PG8_LDB(B0, 0, 0); PG8_SCHED; PG8_LDA(At, 0, 0); PG8_STAGE(PG8_SA(1, 1), a1 + hstepA, voffA);
;             PG8_WAIT_L(8); PG8_BAR; PG8_WAIT_L(0); PG8_MMA(0, 0, At, B0); PG8_BAR; PG8_SCHED;
;             PG8_LDB(B1, 0, 1); PG8_STAGE(PG8_SB(0, 0), b2, voffB);
;             PG8_BAR; PG8_WAIT_L(0); PG8_MMA(0, 1, At, B1); PG8_BAR;
;             PG8_LDA(At, 0, 1); PG8_STAGE(PG8_SA(0, 0), a2, voffA);
;             PG8_BAR; PG8_WAIT_L(0); PG8_MMA(1, 0, At, B0); PG8_BAR; PG8_SCHED;
;             PG8_STAGE(PG8_SB(0, 1), b2 + hstepB, voffB);
;             PG8_WAIT_V(6); PG8_BAR; PG8_MMA(1, 1, At, B1); PG8_BAR;
;             PG8_LDB(B0, 1, 0); PG8_SCHED; PG8_LDA(At, 1, 0); PG8_STAGE(PG8_SA(0, 1), a2 + hstepA, voffA);
;             PG8_WAIT_L(8); PG8_BAR; PG8_WAIT_L(0); PG8_MMA(0, 0, At, B0); PG8_BAR; PG8_SCHED;
;             PG8_LDB(B1, 1, 1); PG8_STAGE(PG8_SB(1, 0), b3, voffB);
;             PG8_BAR; PG8_WAIT_L(0); PG8_MMA(0, 1, At, B1); PG8_BAR;
;             PG8_LDA(At, 1, 1); PG8_STAGE(PG8_SA(1, 0), a3, voffA);
;             PG8_BAR; PG8_WAIT_L(0); PG8_MMA(1, 0, At, B0); PG8_BAR; PG8_SCHED;
;             PG8_STAGE(PG8_SB(1, 1), b3 + hstepB, voffB);
;             PG8_WAIT_V(6); PG8_BAR; PG8_MMA(1, 1, At, B1); PG8_BAR;
;             }
;         }
;         if constexpr (ALIGN_EPI) { if (wr == 0) PG8_BAR; }
;         if constexpr (Epi::FUSED_LAST) { if (has_next) E(acc, cur, wr, wc, fr, fq); }
;         else E(acc, cur, wr, wc, fr, fq);
	s_add_i32 s48, s72, s58
	v_lshl_add_u64 v[200:201], v[200:201], 0, s[14:15]
	s_mov_b32 m0, s48
	ds_read_b128 v[176:179], v162 offset:49152
	ds_read_b128 v[180:183], v162 offset:50176
	ds_read_b128 v[184:187], v162 offset:51200
	ds_read_b128 v[188:191], v162 offset:52224
	ds_read_b128 v[192:195], v162 offset:53248
	ds_read_b128 v[196:199], v162 offset:54272
	ds_read_b128 v[214:217], v162 offset:55296
	ds_read_b128 v[218:221], v162 offset:56320
	global_load_lds_dwordx4 v[200:201], off
	s_add_i32 m0, s48, 0x2000
	s_add_u32 s46, s46, 0x80080
	v_lshl_add_u64 v[200:201], v[222:223], 0, s[14:15]
	s_addc_u32 s47, s47, 0
	s_add_i32 s48, s73, s58
	global_load_lds_dwordx4 v[200:201], off
	v_lshl_add_u64 v[200:201], s[46:47], 0, v[202:203]
	s_mov_b32 m0, s48
	s_nop 0
	global_load_lds_dwordx4 v[200:201], off
	v_lshl_add_u64 v[200:201], s[46:47], 0, v[150:151]
	s_add_i32 m0, s48, 0x2000
	s_nop 0
	global_load_lds_dwordx4 v[200:201], off
	v_lshl_add_u64 v[200:201], v[224:225], 0, s[14:15]
	s_mov_b32 m0, s56
	s_nop 0
	global_load_lds_dwordx4 v[200:201], off
	v_lshl_add_u64 v[200:201], v[226:227], 0, s[14:15]
	s_mov_b32 m0, s62
	s_nop 0
	global_load_lds_dwordx4 v[200:201], off
	s_waitcnt vmcnt(8)
	s_waitcnt lgkmcnt(0)
	s_barrier
	s_waitcnt lgkmcnt(0)
	v_mfma_f32_16x16x32_bf16 v[62:65], v[130:133], v[176:179], v[62:65]
	v_mfma_f32_16x16x32_bf16 v[58:61], v[138:141], v[176:179], v[58:61]
	v_mfma_f32_16x16x32_bf16 v[46:49], v[130:133], v[184:187], v[46:49]
	v_mfma_f32_16x16x32_bf16 v[42:45], v[138:141], v[184:187], v[42:45]
	v_mfma_f32_16x16x32_bf16 v[30:33], v[130:133], v[192:195], v[30:33]
	v_mfma_f32_16x16x32_bf16 v[26:29], v[138:141], v[192:195], v[26:29]
	v_mfma_f32_16x16x32_bf16 v[14:17], v[130:133], v[214:217], v[14:17]
	v_mfma_f32_16x16x32_bf16 v[10:13], v[138:141], v[214:217], v[10:13]
	v_mfma_f32_16x16x32_bf16 v[62:65], v[134:137], v[180:183], v[62:65]
	v_mfma_f32_16x16x32_bf16 v[58:61], v[142:145], v[180:183], v[58:61]
	v_mfma_f32_16x16x32_bf16 v[46:49], v[134:137], v[188:191], v[46:49]
	v_mfma_f32_16x16x32_bf16 v[42:45], v[142:145], v[188:191], v[42:45]
	v_mfma_f32_16x16x32_bf16 v[30:33], v[134:137], v[196:199], v[30:33]
	v_mfma_f32_16x16x32_bf16 v[26:29], v[142:145], v[196:199], v[26:29]
	v_mfma_f32_16x16x32_bf16 v[14:17], v[134:137], v[218:221], v[14:17]
	v_mfma_f32_16x16x32_bf16 v[10:13], v[142:145], v[218:221], v[10:13]
	v_mfma_f32_16x16x32_bf16 v[54:57], v[156:159], v[176:179], v[54:57]
	v_mfma_f32_16x16x32_bf16 v[50:53], v[168:171], v[176:179], v[50:53]
	v_mfma_f32_16x16x32_bf16 v[38:41], v[156:159], v[184:187], v[38:41]
	v_mfma_f32_16x16x32_bf16 v[34:37], v[168:171], v[184:187], v[34:37]
	v_mfma_f32_16x16x32_bf16 v[22:25], v[156:159], v[192:195], v[22:25]
	v_mfma_f32_16x16x32_bf16 v[18:21], v[168:171], v[192:195], v[18:21]
	v_mfma_f32_16x16x32_bf16 v[6:9], v[156:159], v[214:217], v[6:9]
	v_mfma_f32_16x16x32_bf16 v[2:5], v[168:171], v[214:217], v[2:5]
	v_mfma_f32_16x16x32_bf16 v[54:57], v[164:167], v[180:183], v[54:57]
	v_mfma_f32_16x16x32_bf16 v[50:53], v[172:175], v[180:183], v[50:53]
	v_mfma_f32_16x16x32_bf16 v[38:41], v[164:167], v[188:191], v[38:41]
	v_mfma_f32_16x16x32_bf16 v[34:37], v[172:175], v[188:191], v[34:37]
	v_mfma_f32_16x16x32_bf16 v[22:25], v[164:167], v[196:199], v[22:25]
	v_mfma_f32_16x16x32_bf16 v[18:21], v[172:175], v[196:199], v[18:21]
	v_mfma_f32_16x16x32_bf16 v[6:9], v[164:167], v[218:221], v[6:9]
	v_mfma_f32_16x16x32_bf16 v[2:5], v[172:175], v[218:221], v[2:5]
	s_barrier
	s_add_i32 s71, s71, 2
	s_add_u32 s69, s69, 0x100
	s_addc_u32 s70, s70, 0
	s_add_u32 s42, s42, 0x100
	s_addc_u32 s43, s43, 0
	s_cmp_gt_u32 s71, 29
	s_cbranch_scc0 .LBB0_1490
	v_lshl_or_b32 v156, s64, 8, v161
	v_ashrrev_i32_e32 v157, 31, v156
	s_branch .LBB0_1486
